# experiment: nt loads in the FFN-down weight conversion, nt stores for X1 in row pass 1
# speedup vs baseline: 1.0448x; 1.0078x over previous
.LBB0_1063:
	s_waitcnt vmcnt(0)
	v_and_b32_e32 v215, 0xffff0000, v52
	v_and_b32_e32 v217, 0xffff0000, v53
	v_lshlrev_b32_e32 v214, 16, v52
	v_lshlrev_b32_e32 v216, 16, v53
	v_mul_f32_e32 v52, v217, v217
	v_lshlrev_b32_e32 v227, 16, v42
	v_and_b32_e32 v229, 0xffff0000, v42
	v_mul_f32_e32 v42, v215, v215
	v_pk_fma_f32 v[52:53], v[216:217], v[216:217], v[52:53] op_sel_hi:[1,1,0]
	v_and_b32_e32 v221, 0xffff0000, v51
	v_and_b32_e32 v220, 0xffff0000, v50
	v_lshlrev_b32_e32 v230, 16, v43
	v_and_b32_e32 v231, 0xffff0000, v43
	v_pk_fma_f32 v[42:43], v[214:215], v[214:215], v[42:43] op_sel_hi:[1,1,0]
	v_lshlrev_b32_e32 v219, 16, v51
	v_lshlrev_b32_e32 v218, 16, v50
	v_pk_mul_f32 v[50:51], v[220:221], v[220:221]
	v_lshlrev_b32_e32 v222, 16, v44
	v_and_b32_e32 v223, 0xffff0000, v44
	v_lshlrev_b32_e32 v224, 16, v45
	v_and_b32_e32 v225, 0xffff0000, v45
	v_mov_b32_e32 v226, v42
	v_mov_b32_e32 v44, v52
	v_mov_b32_e32 v45, v227
	v_pk_fma_f32 v[50:51], v[218:219], v[218:219], v[50:51]
	v_pk_add_f32 v[42:43], v[42:43], v[52:53]
	v_pk_mul_f32 v[44:45], v[226:227], v[44:45]
	v_mul_f32_e32 v54, v229, v229
	v_mov_b32_e32 v43, v45
	v_pk_add_f32 v[44:45], v[50:51], v[50:51] op_sel:[0,1] op_sel_hi:[1,0]
	v_mul_f32_e32 v50, v225, v225
	v_mov_b32_e32 v45, v54
	v_pk_add_f32 v[42:43], v[42:43], v[44:45]
	v_mul_f32_e32 v44, v223, v223
	v_mul_f32_e32 v55, v230, v230
	v_mul_f32_e32 v56, v231, v231
	v_pk_fma_f32 v[44:45], v[222:223], v[222:223], v[44:45] op_sel_hi:[1,1,0]
	v_pk_fma_f32 v[50:51], v[224:225], v[224:225], v[50:51] op_sel_hi:[1,1,0]
	v_mov_b32_e32 v45, v55
	v_mov_b32_e32 v51, v56
	v_and_b32_e32 v235, 0xffff0000, v41
	v_and_b32_e32 v234, 0xffff0000, v40
	v_pk_add_f32 v[44:45], v[44:45], v[50:51]
	v_lshlrev_b32_e32 v233, 16, v41
	v_lshlrev_b32_e32 v232, 16, v40
	v_pk_mul_f32 v[40:41], v[234:235], v[234:235]
	v_pk_add_f32 v[42:43], v[42:43], v[44:45]
	v_pk_fma_f32 v[40:41], v[232:233], v[232:233], v[40:41]
	v_and_b32_e32 v203, 0xffff0000, v39
	v_pk_add_f32 v[40:41], v[40:41], v[40:41] op_sel:[0,1] op_sel_hi:[1,0]
	v_and_b32_e32 v202, 0xffff0000, v38
	v_lshlrev_b32_e32 v197, 16, v34
	v_and_b32_e32 v195, 0xffff0000, v34
	v_lshlrev_b32_e32 v192, 16, v35
	v_and_b32_e32 v193, 0xffff0000, v35
	v_pk_add_f32 v[34:35], v[42:43], v[42:43] op_sel:[0,1] op_sel_hi:[1,0]
	v_lshlrev_b32_e32 v205, 16, v39
	v_lshlrev_b32_e32 v204, 16, v38
	v_pk_mul_f32 v[38:39], v[202:203], v[202:203]
	v_lshlrev_b32_e32 v198, 16, v36
	v_and_b32_e32 v199, 0xffff0000, v36
	v_lshlrev_b32_e32 v200, 16, v37
	v_and_b32_e32 v201, 0xffff0000, v37
	v_mov_b32_e32 v196, v34
	v_mov_b32_e32 v36, v40
	v_mov_b32_e32 v37, v197
	v_pk_fma_f32 v[38:39], v[204:205], v[204:205], v[38:39]
	v_pk_add_f32 v[34:35], v[34:35], v[40:41]
	v_pk_mul_f32 v[36:37], v[196:197], v[36:37]
	v_mul_f32_e32 v44, v195, v195
	v_mov_b32_e32 v35, v37
	v_pk_add_f32 v[36:37], v[38:39], v[38:39] op_sel:[0,1] op_sel_hi:[1,0]
	v_mul_f32_e32 v38, v201, v201
	v_mov_b32_e32 v37, v44
	v_pk_add_f32 v[34:35], v[34:35], v[36:37]
	v_mul_f32_e32 v36, v199, v199
	v_mul_f32_e32 v45, v192, v192
	v_mul_f32_e32 v50, v193, v193
	v_pk_fma_f32 v[36:37], v[198:199], v[198:199], v[36:37] op_sel_hi:[1,1,0]
	v_pk_fma_f32 v[38:39], v[200:201], v[200:201], v[38:39] op_sel_hi:[1,1,0]
	v_mov_b32_e32 v37, v45
	v_mov_b32_e32 v39, v50
	v_pk_add_f32 v[36:37], v[36:37], v[38:39]
	global_load_dwordx4 v[46:49], v[132:133], off
	global_load_dwordx4 v[62:65], v[132:133], off offset:1024
	v_pk_add_f32 v[34:35], v[34:35], v[36:37]
	global_load_dwordx4 v[58:61], v[132:133], off offset:2048
	global_load_dwordx4 v[54:57], v[132:133], off offset:3072
	v_add_f32_e32 v34, v34, v35
	ds_bpermute_b32 v35, v1, v34
	s_waitcnt lgkmcnt(0)
	v_add_f32_e32 v34, v34, v35
	ds_bpermute_b32 v35, v206, v34
	s_waitcnt lgkmcnt(0)
	v_add_f32_e32 v34, v34, v35
	ds_bpermute_b32 v35, v207, v34
	s_waitcnt lgkmcnt(0)
	v_add_f32_e32 v34, v34, v35
	ds_bpermute_b32 v35, v208, v34
	s_waitcnt lgkmcnt(0)
	v_add_f32_e32 v34, v34, v35
	ds_bpermute_b32 v35, v209, v34
	s_waitcnt lgkmcnt(0)
	v_add_f32_e32 v34, v34, v35
	ds_bpermute_b32 v35, v210, v34
	s_waitcnt lgkmcnt(0)
	v_add_f32_e32 v34, v34, v35
	v_fmamk_f32 v34, v34, 0x3a000000, v211
	v_mul_f32_e32 v35, 0x4f800000, v34
	v_cmp_gt_f32_e32 vcc, s21, v34
	s_nop 1
	v_cndmask_b32_e32 v34, v34, v35, vcc
	v_sqrt_f32_e32 v35, v34
	s_nop 0
	v_add_u32_e32 v36, -1, v35
	v_fma_f32 v37, -v36, v35, v34
	v_cmp_ge_f32_e64 s[0:1], 0, v37
	v_add_u32_e32 v37, 1, v35
	s_nop 0
	v_cndmask_b32_e64 v36, v35, v36, s[0:1]
	v_fma_f32 v35, -v37, v35, v34
	v_cmp_lt_f32_e64 s[0:1], 0, v35
	s_nop 1
	v_cndmask_b32_e64 v35, v36, v37, s[0:1]
	v_mul_f32_e32 v36, 0x37800000, v35
	v_cndmask_b32_e32 v35, v35, v36, vcc
	v_cmp_class_f32_e32 vcc, v34, v212
	s_nop 1
	v_cndmask_b32_e32 v194, v35, v34, vcc
	global_load_dwordx4 v[50:53], v[134:135], off
	global_load_dwordx4 v[42:45], v[136:137], off
	global_load_dwordx4 v[38:41], v[138:139], off
	global_load_dwordx4 v[34:37], v[140:141], off
	v_div_scale_f32 v196, s[0:1], v194, v194, 1.0
	v_rcp_f32_e32 v213, v196
	s_nop 0
	v_fma_f32 v226, -v196, v213, 1.0
	v_fmac_f32_e32 v213, v226, v213
	v_div_scale_f32 v226, vcc, 1.0, v194, 1.0
	v_mul_f32_e32 v228, v226, v213
	v_fma_f32 v236, -v196, v228, v226
	v_fmac_f32_e32 v228, v236, v213
	v_fma_f32 v196, -v196, v228, v226
	v_div_fmas_f32 v196, v196, v213, v228
	v_div_fixup_f32 v196, v196, v194, 1.0
	v_pk_mul_f32 v[214:215], v[196:197], v[214:215] op_sel_hi:[0,1]
	s_waitcnt vmcnt(7)
	v_pk_fma_f32 v[126:127], v[46:47], v[214:215], v[126:127]
	v_pk_mul_f32 v[216:217], v[196:197], v[216:217] op_sel_hi:[0,1]
	v_bfe_u32 v194, v126, 16, 1
	v_add3_u32 v194, v126, v194, s22
	v_bfe_u32 v213, v127, 16, 1
	v_pk_fma_f32 v[128:129], v[48:49], v[216:217], v[128:129]
	v_lshrrev_b32_e32 v194, 16, v194
	v_add3_u32 v213, v127, v213, s22
	v_and_or_b32 v214, v213, s20, v194
	v_bfe_u32 v194, v128, 16, 1
	v_add3_u32 v194, v128, v194, s22
	v_bfe_u32 v213, v129, 16, 1
	v_lshrrev_b32_e32 v194, 16, v194
	v_add3_u32 v213, v129, v213, s22
	v_add_co_u32_e32 v216, vcc, s23, v158
	v_and_or_b32 v215, v213, s20, v194
	s_nop 0
	v_addc_co_u32_e32 v217, vcc, -1, v159, vcc
	global_store_dwordx2 v[216:217], v[214:215], off offset:-3584 nt
	v_mov_b32_e32 v214, v218
	v_mov_b32_e32 v215, v220
	v_mul_f32_e32 v194, v127, v127
	v_mul_f32_e32 v213, v129, v129
	v_pk_mul_f32 v[214:215], v[196:197], v[214:215] op_sel_hi:[0,1]
	v_fmac_f32_e32 v194, v126, v126
	v_fmac_f32_e32 v213, v128, v128
	s_waitcnt vmcnt(7)
	v_pk_fma_f32 v[122:123], v[62:63], v[214:215], v[122:123]
	v_add_f32_e32 v194, v194, v213
	v_mov_b32_e32 v220, v219
	v_bfe_u32 v213, v122, 16, 1
	v_pk_mul_f32 v[218:219], v[196:197], v[220:221] op_sel_hi:[0,1]
	v_add3_u32 v213, v122, v213, s22
	v_bfe_u32 v214, v123, 16, 1
	v_pk_fma_f32 v[124:125], v[64:65], v[218:219], v[124:125]
	v_lshrrev_b32_e32 v213, 16, v213
	v_add3_u32 v214, v123, v214, s22
	v_and_or_b32 v214, v214, s20, v213
	v_bfe_u32 v213, v124, 16, 1
	v_add3_u32 v213, v124, v213, s22
	v_bfe_u32 v215, v125, 16, 1
	v_lshrrev_b32_e32 v213, 16, v213
	v_add3_u32 v215, v125, v215, s22
	v_and_or_b32 v215, v215, s20, v213
	global_store_dwordx2 v[216:217], v[214:215], off offset:-3072 nt
	v_mul_f32_e32 v213, v123, v123
	v_mul_f32_e32 v214, v125, v125
	v_fmac_f32_e32 v213, v122, v122
	v_fmac_f32_e32 v214, v124, v124
	v_add_f32_e32 v213, v213, v214
	v_pk_mul_f32 v[214:215], v[196:197], v[222:223] op_sel_hi:[0,1]
	s_waitcnt vmcnt(7)
	v_pk_fma_f32 v[118:119], v[58:59], v[214:215], v[118:119]
	v_add_f32_e32 v194, v194, v213
	v_bfe_u32 v213, v118, 16, 1
	v_pk_mul_f32 v[218:219], v[196:197], v[224:225] op_sel_hi:[0,1]
	v_add3_u32 v213, v118, v213, s22
	v_bfe_u32 v214, v119, 16, 1
	v_pk_fma_f32 v[120:121], v[60:61], v[218:219], v[120:121]
	v_lshrrev_b32_e32 v213, 16, v213
	v_add3_u32 v214, v119, v214, s22
	v_and_or_b32 v214, v214, s20, v213
	v_bfe_u32 v213, v120, 16, 1
	v_add3_u32 v213, v120, v213, s22
	v_bfe_u32 v215, v121, 16, 1
	v_lshrrev_b32_e32 v213, 16, v213
	v_add3_u32 v215, v121, v215, s22
	v_and_or_b32 v215, v215, s20, v213
	global_store_dwordx2 v[216:217], v[214:215], off offset:-2560 nt
	v_mul_f32_e32 v213, v119, v119
	v_mul_f32_e32 v214, v121, v121
	v_fmac_f32_e32 v213, v118, v118
	v_fmac_f32_e32 v214, v120, v120
	v_mov_b32_e32 v228, v227
	v_add_f32_e32 v213, v213, v214
	v_pk_mul_f32 v[214:215], v[196:197], v[228:229] op_sel_hi:[0,1]
	s_waitcnt vmcnt(7)
	v_pk_fma_f32 v[114:115], v[54:55], v[214:215], v[114:115]
	v_add_f32_e32 v194, v213, v194
	v_bfe_u32 v213, v114, 16, 1
	v_pk_mul_f32 v[218:219], v[196:197], v[230:231] op_sel_hi:[0,1]
	v_add3_u32 v213, v114, v213, s22
	v_bfe_u32 v214, v115, 16, 1
	v_pk_fma_f32 v[116:117], v[56:57], v[218:219], v[116:117]
	v_lshrrev_b32_e32 v213, 16, v213
	v_add3_u32 v214, v115, v214, s22
	v_and_or_b32 v214, v214, s20, v213
	v_bfe_u32 v213, v116, 16, 1
	v_add3_u32 v213, v116, v213, s22
	v_bfe_u32 v215, v117, 16, 1
	v_lshrrev_b32_e32 v213, 16, v213
	v_add3_u32 v215, v117, v215, s22
	v_and_or_b32 v215, v215, s20, v213
	global_store_dwordx2 v[216:217], v[214:215], off offset:-2048 nt
	v_mul_f32_e32 v213, v115, v115
	v_mul_f32_e32 v214, v117, v117
	v_fmac_f32_e32 v213, v114, v114
	v_fmac_f32_e32 v214, v116, v116
	v_add_f32_e32 v213, v213, v214
	v_mov_b32_e32 v214, v232
	v_mov_b32_e32 v215, v234
	v_pk_mul_f32 v[214:215], v[196:197], v[214:215] op_sel_hi:[0,1]
	s_waitcnt vmcnt(7)
	v_pk_fma_f32 v[110:111], v[50:51], v[214:215], v[110:111]
	v_add_f32_e32 v194, v213, v194
	v_mov_b32_e32 v234, v233
	v_bfe_u32 v213, v110, 16, 1
	v_pk_mul_f32 v[218:219], v[196:197], v[234:235] op_sel_hi:[0,1]
	v_add3_u32 v213, v110, v213, s22
	v_bfe_u32 v214, v111, 16, 1
	v_pk_fma_f32 v[112:113], v[52:53], v[218:219], v[112:113]
	v_lshrrev_b32_e32 v213, 16, v213
	v_add3_u32 v214, v111, v214, s22
	v_and_or_b32 v214, v214, s20, v213
	v_bfe_u32 v213, v112, 16, 1
	v_add3_u32 v213, v112, v213, s22
	v_bfe_u32 v215, v113, 16, 1
	v_lshrrev_b32_e32 v213, 16, v213
	v_add3_u32 v215, v113, v215, s22
	v_and_or_b32 v215, v215, s20, v213
	global_store_dwordx2 v[216:217], v[214:215], off offset:-1536 nt
	v_mul_f32_e32 v213, v111, v111
	v_mul_f32_e32 v214, v113, v113
	v_fmac_f32_e32 v213, v110, v110
	v_fmac_f32_e32 v214, v112, v112
	v_add_f32_e32 v213, v213, v214
	v_mov_b32_e32 v214, v204
	v_mov_b32_e32 v215, v202
	v_pk_mul_f32 v[214:215], v[196:197], v[214:215] op_sel_hi:[0,1]
	v_mov_b32_e32 v202, v205
	v_pk_mul_f32 v[202:203], v[196:197], v[202:203] op_sel_hi:[0,1]
	s_waitcnt vmcnt(7)
	v_pk_fma_f32 v[106:107], v[42:43], v[214:215], v[106:107]
	v_pk_mul_f32 v[198:199], v[196:197], v[198:199] op_sel_hi:[0,1]
	v_pk_fma_f32 v[108:109], v[44:45], v[202:203], v[108:109]
	v_bfe_u32 v202, v106, 16, 1
	s_waitcnt vmcnt(6)
	v_pk_fma_f32 v[102:103], v[38:39], v[198:199], v[102:103]
	v_add3_u32 v202, v106, v202, s22
	v_bfe_u32 v203, v107, 16, 1
	v_bfe_u32 v198, v102, 16, 1
	v_lshrrev_b32_e32 v202, 16, v202
	v_add3_u32 v203, v107, v203, s22
	v_pk_mul_f32 v[200:201], v[196:197], v[200:201] op_sel_hi:[0,1]
	v_add3_u32 v198, v102, v198, s22
	v_bfe_u32 v199, v103, 16, 1
	v_and_or_b32 v202, v203, s20, v202
	v_bfe_u32 v203, v108, 16, 1
	v_pk_fma_f32 v[104:105], v[40:41], v[200:201], v[104:105]
	v_lshrrev_b32_e32 v198, 16, v198
	v_add3_u32 v199, v103, v199, s22
	v_add3_u32 v203, v108, v203, s22
	v_bfe_u32 v204, v109, 16, 1
	v_and_or_b32 v198, v199, s20, v198
	v_bfe_u32 v199, v104, 16, 1
	v_lshrrev_b32_e32 v203, 16, v203
	v_add3_u32 v204, v109, v204, s22
	v_add3_u32 v199, v104, v199, s22
	v_bfe_u32 v200, v105, 16, 1
	v_and_or_b32 v203, v204, s20, v203
	v_lshrrev_b32_e32 v199, 16, v199
	v_add3_u32 v200, v105, v200, s22
	global_store_dwordx2 v[216:217], v[202:203], off offset:-1024 nt
	v_mul_f32_e32 v202, v107, v107
	v_mul_f32_e32 v203, v109, v109
	v_and_or_b32 v199, v200, s20, v199
	v_fmac_f32_e32 v202, v106, v106
	v_fmac_f32_e32 v203, v108, v108
	global_store_dwordx2 v[216:217], v[198:199], off offset:-512 nt
	v_mul_f32_e32 v198, v103, v103
	v_mul_f32_e32 v199, v105, v105
	v_add_f32_e32 v194, v213, v194
	v_add_f32_e32 v202, v202, v203
	v_fmac_f32_e32 v198, v102, v102
	v_fmac_f32_e32 v199, v104, v104
	v_add_f32_e32 v194, v202, v194
	v_add_f32_e32 v198, v198, v199
	v_add_f32_e32 v198, v198, v194
	v_mov_b32_e32 v194, v197
	v_pk_mul_f32 v[194:195], v[196:197], v[194:195] op_sel_hi:[0,1]
	v_pk_mul_f32 v[192:193], v[196:197], v[192:193] op_sel_hi:[0,1]
	s_waitcnt vmcnt(7)
	v_pk_fma_f32 v[98:99], v[34:35], v[194:195], v[98:99]
	v_pk_fma_f32 v[100:101], v[36:37], v[192:193], v[100:101]
	v_bfe_u32 v192, v98, 16, 1
	v_add3_u32 v192, v98, v192, s22
	v_bfe_u32 v193, v99, 16, 1
	v_lshrrev_b32_e32 v192, 16, v192
	v_add3_u32 v193, v99, v193, s22
	v_and_or_b32 v192, v193, s20, v192
	v_bfe_u32 v193, v100, 16, 1
	v_add3_u32 v193, v100, v193, s22
	v_bfe_u32 v194, v101, 16, 1
	v_lshrrev_b32_e32 v193, 16, v193
	v_add3_u32 v194, v101, v194, s22
	v_and_or_b32 v193, v194, s20, v193
	global_store_dwordx2 v[216:217], v[192:193], off nt
	ds_read_b128 v[192:195], v253
	v_mul_f32_e32 v196, v99, v99
	v_mul_f32_e32 v197, v101, v101
	v_fmac_f32_e32 v196, v98, v98
	v_fmac_f32_e32 v197, v100, v100
	v_add_f32_e32 v196, v196, v197
	v_add_f32_e32 v196, v196, v198
	ds_bpermute_b32 v197, v1, v196
	s_waitcnt lgkmcnt(0)
	v_add_f32_e32 v196, v196, v197
	ds_bpermute_b32 v197, v206, v196
	s_waitcnt lgkmcnt(0)
	v_add_f32_e32 v196, v196, v197
	ds_bpermute_b32 v197, v207, v196
	s_waitcnt lgkmcnt(0)
	v_add_f32_e32 v196, v196, v197
	ds_bpermute_b32 v197, v208, v196
	s_waitcnt lgkmcnt(0)
	v_add_f32_e32 v196, v196, v197
	ds_bpermute_b32 v197, v209, v196
	s_waitcnt lgkmcnt(0)
	v_add_f32_e32 v196, v196, v197
	ds_bpermute_b32 v197, v210, v196
	s_waitcnt lgkmcnt(0)
	v_add_f32_e32 v196, v196, v197
	v_fmamk_f32 v196, v196, 0x3a000000, v211
	v_mul_f32_e32 v197, 0x4f800000, v196
	v_cmp_gt_f32_e32 vcc, s21, v196
	s_nop 1
	v_cndmask_b32_e32 v196, v196, v197, vcc
	v_sqrt_f32_e32 v197, v196
	s_nop 0
	v_add_u32_e32 v198, -1, v197
	v_fma_f32 v199, -v198, v197, v196
	v_cmp_ge_f32_e64 s[0:1], 0, v199
	v_add_u32_e32 v199, 1, v197
	s_nop 0
	v_cndmask_b32_e64 v198, v197, v198, s[0:1]
	v_fma_f32 v197, -v199, v197, v196
	v_cmp_lt_f32_e64 s[0:1], 0, v197
	s_nop 1
	v_cndmask_b32_e64 v197, v198, v199, s[0:1]
	v_mul_f32_e32 v198, 0x37800000, v197
	v_cndmask_b32_e32 v197, v197, v198, vcc
	v_cmp_class_f32_e32 vcc, v196, v212
	s_nop 1
	v_cndmask_b32_e32 v196, v197, v196, vcc
	v_div_scale_f32 v197, s[0:1], v196, v196, 1.0
	v_rcp_f32_e32 v198, v197
	s_nop 0
	v_fma_f32 v199, -v197, v198, 1.0
	v_fmac_f32_e32 v198, v199, v198
	v_div_scale_f32 v199, vcc, 1.0, v196, 1.0
	v_mul_f32_e32 v200, v199, v198
	v_fma_f32 v201, -v197, v200, v199
	v_fmac_f32_e32 v200, v201, v198
	v_fma_f32 v197, -v197, v200, v199
	v_div_fmas_f32 v197, v197, v198, v200
	v_div_fixup_f32 v196, v197, v196, 1.0
	v_mul_f32_e32 v126, v126, v196
	s_waitcnt lgkmcnt(0)
	v_mul_f32_e32 v126, v192, v126
	v_mul_f32_e32 v127, v127, v196
	v_mul_f32_e32 v127, v193, v127
	v_bfe_u32 v192, v126, 16, 1
	v_add3_u32 v126, v126, v192, s22
	v_bfe_u32 v192, v127, 16, 1
	v_lshrrev_b32_e32 v126, 16, v126
	v_add3_u32 v127, v127, v192, s22
	v_and_or_b32 v126, v127, s20, v126
	v_mul_f32_e32 v127, v128, v196
	v_mul_f32_e32 v127, v194, v127
	v_mul_f32_e32 v128, v129, v196
	v_mul_f32_e32 v128, v195, v128
	v_bfe_u32 v129, v127, 16, 1
	v_add3_u32 v127, v127, v129, s22
	v_bfe_u32 v129, v128, 16, 1
	v_lshrrev_b32_e32 v127, 16, v127
	v_add3_u32 v128, v128, v129, s22
	v_and_or_b32 v127, v128, s20, v127
	global_store_dwordx2 v[158:159], v[126:127], off offset:-3584
	ds_read_b128 v[126:129], v253 offset:1024
	v_mul_f32_e32 v122, v122, v196
	v_mul_f32_e32 v123, v123, v196
	v_mul_f32_e32 v118, v118, v196
	v_mul_f32_e32 v119, v119, v196
	v_mul_f32_e32 v114, v114, v196
	v_mul_f32_e32 v115, v115, v196
	v_mul_f32_e32 v110, v110, v196
	v_mul_f32_e32 v112, v112, v196
	v_mul_f32_e32 v111, v111, v196
	v_mul_f32_e32 v113, v113, v196
	v_mul_f32_e32 v106, v106, v196
	v_mul_f32_e32 v108, v108, v196
	v_mul_f32_e32 v107, v107, v196
	v_mul_f32_e32 v109, v109, v196
	v_mul_f32_e32 v102, v102, v196
	v_mul_f32_e32 v104, v104, v196
	v_mul_f32_e32 v103, v103, v196
	v_mul_f32_e32 v105, v105, v196
	v_mul_f32_e32 v98, v98, v196
	v_mul_f32_e32 v100, v100, v196
	v_mul_f32_e32 v99, v99, v196
	v_mul_f32_e32 v101, v101, v196
	s_andn2_b64 vcc, exec, s[14:15]
	s_waitcnt lgkmcnt(0)
	v_mul_f32_e32 v122, v126, v122
	v_mul_f32_e32 v123, v127, v123
	v_bfe_u32 v126, v122, 16, 1
	v_add3_u32 v122, v122, v126, s22
	v_bfe_u32 v126, v123, 16, 1
	v_lshrrev_b32_e32 v122, 16, v122
	v_add3_u32 v123, v123, v126, s22
	v_and_or_b32 v122, v123, s20, v122
	v_mul_f32_e32 v123, v124, v196
	v_mul_f32_e32 v123, v128, v123
	v_mul_f32_e32 v124, v125, v196
	v_mul_f32_e32 v124, v129, v124
	v_bfe_u32 v125, v123, 16, 1
	v_add3_u32 v123, v123, v125, s22
	v_bfe_u32 v125, v124, 16, 1
	v_lshrrev_b32_e32 v123, 16, v123
	v_add3_u32 v124, v124, v125, s22
	v_and_or_b32 v123, v124, s20, v123
	global_store_dwordx2 v[158:159], v[122:123], off offset:-3072
	ds_read_b128 v[122:125], v253 offset:2048
	s_waitcnt lgkmcnt(0)
	v_mul_f32_e32 v118, v122, v118
	v_mul_f32_e32 v119, v123, v119
	v_bfe_u32 v122, v118, 16, 1
	v_add3_u32 v118, v118, v122, s22
	v_bfe_u32 v122, v119, 16, 1
	v_lshrrev_b32_e32 v118, 16, v118
	v_add3_u32 v119, v119, v122, s22
	v_and_or_b32 v118, v119, s20, v118
	v_mul_f32_e32 v119, v120, v196
	v_mul_f32_e32 v119, v124, v119
	v_mul_f32_e32 v120, v121, v196
	v_mul_f32_e32 v120, v125, v120
	v_bfe_u32 v121, v119, 16, 1
	v_add3_u32 v119, v119, v121, s22
	v_bfe_u32 v121, v120, 16, 1
	v_lshrrev_b32_e32 v119, 16, v119
	v_add3_u32 v120, v120, v121, s22
	v_and_or_b32 v119, v120, s20, v119
	global_store_dwordx2 v[158:159], v[118:119], off offset:-2560
	ds_read_b128 v[118:121], v253 offset:3072
	s_waitcnt lgkmcnt(0)
	v_mul_f32_e32 v114, v118, v114
	v_mul_f32_e32 v115, v119, v115
	v_bfe_u32 v118, v114, 16, 1
	v_add3_u32 v114, v114, v118, s22
	v_bfe_u32 v118, v115, 16, 1
	v_lshrrev_b32_e32 v114, 16, v114
	v_add3_u32 v115, v115, v118, s22
	v_and_or_b32 v114, v115, s20, v114
	v_mul_f32_e32 v115, v116, v196
	v_mul_f32_e32 v115, v120, v115
	v_mul_f32_e32 v116, v117, v196
	v_mul_f32_e32 v116, v121, v116
	v_bfe_u32 v117, v115, 16, 1
	v_add3_u32 v115, v115, v117, s22
	v_bfe_u32 v117, v116, 16, 1
	v_lshrrev_b32_e32 v115, 16, v115
	v_add3_u32 v116, v116, v117, s22
	v_and_or_b32 v115, v116, s20, v115
	global_store_dwordx2 v[158:159], v[114:115], off offset:-2048
	ds_read_b128 v[114:117], v253 offset:4096
	s_waitcnt lgkmcnt(0)
	v_mul_f32_e32 v110, v114, v110
	v_mul_f32_e32 v112, v116, v112
	v_mul_f32_e32 v111, v115, v111
	v_mul_f32_e32 v113, v117, v113
	v_bfe_u32 v114, v110, 16, 1
	v_bfe_u32 v116, v112, 16, 1
	v_bfe_u32 v115, v111, 16, 1
	v_bfe_u32 v117, v113, 16, 1
	v_add3_u32 v110, v110, v114, s22
	v_add3_u32 v112, v112, v116, s22
	v_add3_u32 v111, v111, v115, s22
	v_add3_u32 v113, v113, v117, s22
	v_lshrrev_b32_e32 v110, 16, v110
	v_lshrrev_b32_e32 v112, 16, v112
	v_and_or_b32 v110, v111, s20, v110
	v_and_or_b32 v111, v113, s20, v112
	global_store_dwordx2 v[158:159], v[110:111], off offset:-1536
	ds_read_b128 v[110:113], v253 offset:5120
	s_waitcnt lgkmcnt(0)
	v_mul_f32_e32 v106, v110, v106
	v_mul_f32_e32 v108, v112, v108
	v_mul_f32_e32 v107, v111, v107
	v_mul_f32_e32 v109, v113, v109
	v_bfe_u32 v110, v106, 16, 1
	v_bfe_u32 v112, v108, 16, 1
	v_bfe_u32 v111, v107, 16, 1
	v_bfe_u32 v113, v109, 16, 1
	v_add3_u32 v106, v106, v110, s22
	v_add3_u32 v108, v108, v112, s22
	v_add3_u32 v107, v107, v111, s22
	v_add3_u32 v109, v109, v113, s22
	v_lshrrev_b32_e32 v106, 16, v106
	v_lshrrev_b32_e32 v108, 16, v108
	v_and_or_b32 v106, v107, s20, v106
	v_and_or_b32 v107, v109, s20, v108
	global_store_dwordx2 v[158:159], v[106:107], off offset:-1024
	ds_read_b128 v[106:109], v253 offset:6144
	s_waitcnt lgkmcnt(0)
	v_mul_f32_e32 v102, v106, v102
	v_mul_f32_e32 v104, v108, v104
	v_mul_f32_e32 v103, v107, v103
	v_mul_f32_e32 v105, v109, v105
	v_bfe_u32 v106, v102, 16, 1
	v_bfe_u32 v108, v104, 16, 1
	v_bfe_u32 v107, v103, 16, 1
	v_bfe_u32 v109, v105, 16, 1
	v_add3_u32 v102, v102, v106, s22
	v_add3_u32 v104, v104, v108, s22
	v_add3_u32 v103, v103, v107, s22
	v_add3_u32 v105, v105, v109, s22
	v_lshrrev_b32_e32 v102, 16, v102
	v_lshrrev_b32_e32 v104, 16, v104
	v_and_or_b32 v102, v103, s20, v102
	v_and_or_b32 v103, v105, s20, v104
	global_store_dwordx2 v[158:159], v[102:103], off offset:-512
	ds_read_b128 v[102:105], v253 offset:7168
	s_waitcnt lgkmcnt(0)
	v_mul_f32_e32 v98, v102, v98
	v_mul_f32_e32 v100, v104, v100
	v_mul_f32_e32 v99, v103, v99
	v_mul_f32_e32 v101, v105, v101
	v_bfe_u32 v102, v98, 16, 1
	v_bfe_u32 v104, v100, 16, 1
	v_bfe_u32 v103, v99, 16, 1
	v_bfe_u32 v105, v101, 16, 1
	v_add3_u32 v98, v98, v102, s22
	v_add3_u32 v100, v100, v104, s22
	v_add3_u32 v99, v99, v103, s22
	v_add3_u32 v101, v101, v105, s22
	v_lshrrev_b32_e32 v98, 16, v98
	v_lshrrev_b32_e32 v100, 16, v100
	v_and_or_b32 v98, v99, s20, v98
	v_and_or_b32 v99, v101, s20, v100
	global_store_dwordx2 v[158:159], v[98:99], off
	s_cbranch_vccnz .LBB0_1065
	v_and_b32_e32 v119, 0xffff0000, v190
	v_and_b32_e32 v118, 0xffff0000, v188
	v_and_b32_e32 v123, 0xffff0000, v191
	v_and_b32_e32 v122, 0xffff0000, v189
	v_lshlrev_b32_e32 v117, 16, v190
	v_lshlrev_b32_e32 v116, 16, v188
	v_lshlrev_b32_e32 v121, 16, v191
	v_lshlrev_b32_e32 v120, 16, v189
	v_pk_mul_f32 v[98:99], v[118:119], v[118:119]
	v_pk_mul_f32 v[100:101], v[122:123], v[122:123]
	v_pk_fma_f32 v[98:99], v[116:117], v[116:117], v[98:99]
	v_pk_fma_f32 v[100:101], v[120:121], v[120:121], v[100:101]
	v_and_b32_e32 v127, 0xffff0000, v187
	v_pk_add_f32 v[98:99], v[98:99], v[100:101]
	v_and_b32_e32 v126, 0xffff0000, v186
	v_pk_add_f32 v[98:99], v[98:99], v[98:99] op_sel_hi:[0,1]
	v_lshlrev_b32_e32 v125, 16, v187
	v_lshlrev_b32_e32 v124, 16, v186
	v_pk_mul_f32 v[100:101], v[126:127], v[126:127]
	v_lshlrev_b32_e32 v128, 16, v184
	v_and_b32_e32 v129, 0xffff0000, v184
	v_lshlrev_b32_e32 v184, 16, v185
	v_lshlrev_b32_e32 v112, 16, v182
	v_pk_fma_f32 v[100:101], v[124:125], v[124:125], v[100:101]
	v_and_b32_e32 v185, 0xffff0000, v185
	v_mul_f32_e32 v113, v128, v128
	v_mul_f32_e32 v103, v129, v129
	v_mul_f32_e32 v98, v184, v184
	v_mov_b32_e32 v102, v112
	v_pk_add_f32 v[100:101], v[100:101], v[100:101] op_sel_hi:[0,1]
	v_pk_fma_f32 v[104:105], v[184:185], v[184:185], v[98:99] op_sel_hi:[1,1,0]
	v_and_b32_e32 v186, 0xffff0000, v182
	v_lshlrev_b32_e32 v114, 16, v183
	v_and_b32_e32 v115, 0xffff0000, v183
	v_pk_add_f32 v[102:103], v[112:113], v[102:103]
	v_mul_f32_e32 v104, v186, v186
	v_mul_f32_e32 v100, v114, v114
	v_mul_f32_e32 v98, v115, v115
	v_mul_f32_e32 v106, v112, v112
	v_mov_b32_e32 v107, v103
	v_pk_add_f32 v[102:103], v[106:107], v[104:105]
	v_pk_add_f32 v[98:99], v[100:101], v[98:99]
	v_and_b32_e32 v109, 0xffff0000, v181
	v_pk_add_f32 v[98:99], v[102:103], v[98:99]
	v_and_b32_e32 v108, 0xffff0000, v180
	v_pk_add_f32 v[106:107], v[98:99], v[98:99] op_sel_hi:[0,1]
	v_lshlrev_b32_e32 v111, 16, v181
	v_lshlrev_b32_e32 v110, 16, v180
	v_pk_mul_f32 v[98:99], v[108:109], v[108:109]
	v_lshlrev_b32_e32 v102, 16, v178
	v_pk_fma_f32 v[98:99], v[110:111], v[110:111], v[98:99]
	v_lshlrev_b32_e32 v104, 16, v179
	v_pk_add_f32 v[180:181], v[98:99], v[98:99] op_sel_hi:[0,1]
	v_and_b32_e32 v105, 0xffff0000, v179
	v_mul_f32_e32 v99, v102, v102
	v_mul_f32_e32 v98, v104, v104
	v_and_b32_e32 v103, 0xffff0000, v178
	v_pk_fma_f32 v[182:183], v[104:105], v[104:105], v[98:99] op_sel_hi:[1,1,0]
	v_lshlrev_b32_e32 v98, 16, v176
	v_mul_f32_e32 v179, v103, v103
	v_mov_b32_e32 v178, v98
	v_and_b32_e32 v187, 0xffff0000, v176
	v_lshlrev_b32_e32 v100, 16, v177
	v_and_b32_e32 v101, 0xffff0000, v177
	v_pk_add_f32 v[178:179], v[98:99], v[178:179]
	v_mul_f32_e32 v182, v187, v187
	v_mul_f32_e32 v180, v100, v100
	v_mul_f32_e32 v106, v101, v101
	v_mul_f32_e32 v176, v98, v98
	v_mov_b32_e32 v177, v179
	v_pk_add_f32 v[176:177], v[176:177], v[182:183]
	v_pk_add_f32 v[106:107], v[180:181], v[106:107]
	v_mov_b32_e32 v180, v121
	v_pk_add_f32 v[106:107], v[176:177], v[106:107]
	v_mov_b32_e32 v181, v123
	v_add_f32_e32 v99, v106, v107
	ds_bpermute_b32 v106, v1, v99
	v_mov_b32_e32 v121, v122
	s_ashr_i32 s13, s12, 31
	s_lshl_b64 s[12:13], s[12:13], 12
	s_waitcnt lgkmcnt(0)
	v_add_f32_e32 v99, v99, v106
	ds_bpermute_b32 v106, v206, v99
	s_waitcnt lgkmcnt(0)
	v_add_f32_e32 v99, v99, v106
	ds_bpermute_b32 v106, v207, v99
	s_waitcnt lgkmcnt(0)
	v_add_f32_e32 v99, v99, v106
	ds_bpermute_b32 v106, v208, v99
	s_waitcnt lgkmcnt(0)
	v_add_f32_e32 v99, v99, v106
	ds_bpermute_b32 v106, v209, v99
	s_waitcnt lgkmcnt(0)
	v_add_f32_e32 v99, v99, v106
	ds_bpermute_b32 v106, v210, v99
	s_waitcnt lgkmcnt(0)
	v_add_f32_e32 v99, v99, v106
	v_fmamk_f32 v99, v99, 0x3a000000, v211
	v_mul_f32_e32 v106, 0x4f800000, v99
	v_cmp_gt_f32_e32 vcc, s21, v99
	s_nop 1
	v_cndmask_b32_e32 v99, v99, v106, vcc
	v_sqrt_f32_e32 v106, v99
	s_nop 0
	v_add_u32_e32 v107, -1, v106
	v_fma_f32 v113, -v107, v106, v99
	v_cmp_ge_f32_e64 s[0:1], 0, v113
	v_add_u32_e32 v113, 1, v106
	s_nop 0
	v_cndmask_b32_e64 v107, v106, v107, s[0:1]
	v_fma_f32 v106, -v113, v106, v99
	v_cmp_lt_f32_e64 s[0:1], 0, v106
	s_nop 1
	v_cndmask_b32_e64 v106, v107, v113, s[0:1]
	v_mul_f32_e32 v107, 0x37800000, v106
	v_cndmask_b32_e32 v106, v106, v107, vcc
	v_cmp_class_f32_e32 vcc, v99, v212
	s_nop 1
	v_cndmask_b32_e32 v99, v106, v99, vcc
	v_div_scale_f32 v113, s[0:1], v99, v99, 1.0
	v_rcp_f32_e32 v176, v113
	v_lshl_add_u64 v[106:107], v[154:155], 0, s[12:13]
	v_fma_f32 v177, -v113, v176, 1.0
	v_fmac_f32_e32 v176, v177, v176
	v_div_scale_f32 v177, vcc, 1.0, v99, 1.0
	v_mul_f32_e32 v178, v177, v176
	v_fma_f32 v179, -v113, v178, v177
	v_fmac_f32_e32 v178, v179, v176
	v_fma_f32 v113, -v113, v178, v177
	v_div_fmas_f32 v113, v113, v176, v178
	v_div_fixup_f32 v176, v113, v99, 1.0
	v_mov_b32_e32 v178, v117
	v_mov_b32_e32 v179, v119
	v_pk_mul_f32 v[178:179], v[176:177], v[178:179] op_sel_hi:[0,1]
	v_pk_fma_f32 v[94:95], v[46:47], v[178:179], v[94:95]
	v_pk_mul_f32 v[180:181], v[176:177], v[180:181] op_sel_hi:[0,1]
	v_bfe_u32 v99, v94, 16, 1
	v_add3_u32 v99, v94, v99, s22
	v_bfe_u32 v113, v95, 16, 1
	v_pk_fma_f32 v[96:97], v[48:49], v[180:181], v[96:97]
	v_lshrrev_b32_e32 v99, 16, v99
	v_add3_u32 v113, v95, v113, s22
	v_and_or_b32 v178, v113, s20, v99
	v_bfe_u32 v99, v96, 16, 1
	v_add3_u32 v99, v96, v99, s22
	v_bfe_u32 v113, v97, 16, 1
	v_lshrrev_b32_e32 v99, 16, v99
	v_add3_u32 v113, v97, v113, s22
	v_mov_b32_e32 v117, v118
	v_and_or_b32 v179, v113, s20, v99
	v_mul_f32_e32 v99, v95, v95
	v_mul_f32_e32 v113, v97, v97
	v_pk_mul_f32 v[116:117], v[176:177], v[116:117] op_sel_hi:[0,1]
	v_fmac_f32_e32 v99, v94, v94
	v_fmac_f32_e32 v113, v96, v96
	v_pk_fma_f32 v[90:91], v[62:63], v[116:117], v[90:91]
	v_add_f32_e32 v99, v99, v113
	v_bfe_u32 v113, v90, 16, 1
	v_pk_mul_f32 v[118:119], v[176:177], v[120:121] op_sel_hi:[0,1]
	v_add3_u32 v113, v90, v113, s22
	v_bfe_u32 v116, v91, 16, 1
	v_pk_fma_f32 v[92:93], v[64:65], v[118:119], v[92:93]
	v_lshrrev_b32_e32 v113, 16, v113
	v_add3_u32 v116, v91, v116, s22
	v_and_or_b32 v116, v116, s20, v113
	v_bfe_u32 v113, v92, 16, 1
	v_add3_u32 v113, v92, v113, s22
	v_bfe_u32 v117, v93, 16, 1
	v_lshrrev_b32_e32 v113, 16, v113
	v_add3_u32 v117, v93, v117, s22
	v_and_or_b32 v117, v117, s20, v113
	global_store_dwordx2 v[106:107], v[116:117], off offset:512 nt
	v_mul_f32_e32 v113, v91, v91
	v_mul_f32_e32 v116, v93, v93
	v_fmac_f32_e32 v113, v90, v90
	v_fmac_f32_e32 v116, v92, v92
	v_add_f32_e32 v113, v113, v116
	v_mov_b32_e32 v116, v124
	v_mov_b32_e32 v117, v126
	v_pk_mul_f32 v[116:117], v[176:177], v[116:117] op_sel_hi:[0,1]
	v_pk_fma_f32 v[86:87], v[58:59], v[116:117], v[86:87]
	v_add_f32_e32 v99, v99, v113
	v_mov_b32_e32 v126, v125
	v_bfe_u32 v113, v86, 16, 1
	v_pk_mul_f32 v[118:119], v[176:177], v[126:127] op_sel_hi:[0,1]
	v_add3_u32 v113, v86, v113, s22
	v_bfe_u32 v116, v87, 16, 1
	v_pk_fma_f32 v[88:89], v[60:61], v[118:119], v[88:89]
	v_lshrrev_b32_e32 v113, 16, v113
	v_add3_u32 v116, v87, v116, s22
	v_and_or_b32 v116, v116, s20, v113
	v_bfe_u32 v113, v88, 16, 1
	v_add3_u32 v113, v88, v113, s22
	v_bfe_u32 v117, v89, 16, 1
	v_lshrrev_b32_e32 v113, 16, v113
	v_add3_u32 v117, v89, v117, s22
	v_and_or_b32 v117, v117, s20, v113
	global_store_dwordx2 v[106:107], v[116:117], off offset:1024 nt
	v_mul_f32_e32 v113, v87, v87
	v_mul_f32_e32 v116, v89, v89
	v_fmac_f32_e32 v113, v86, v86
	v_fmac_f32_e32 v116, v88, v88
	v_add_f32_e32 v113, v113, v116
	v_pk_mul_f32 v[116:117], v[176:177], v[128:129] op_sel_hi:[0,1]
	v_pk_fma_f32 v[82:83], v[54:55], v[116:117], v[82:83]
	v_add_f32_e32 v99, v113, v99
	v_bfe_u32 v113, v82, 16, 1
	v_pk_mul_f32 v[118:119], v[176:177], v[184:185] op_sel_hi:[0,1]
	v_add3_u32 v113, v82, v113, s22
	v_bfe_u32 v116, v83, 16, 1
	v_pk_fma_f32 v[84:85], v[56:57], v[118:119], v[84:85]
	v_lshrrev_b32_e32 v113, 16, v113
	v_add3_u32 v116, v83, v116, s22
	v_and_or_b32 v116, v116, s20, v113
	v_bfe_u32 v113, v84, 16, 1
	v_add3_u32 v113, v84, v113, s22
	v_bfe_u32 v117, v85, 16, 1
	v_lshrrev_b32_e32 v113, 16, v113
	v_add3_u32 v117, v85, v117, s22
	v_and_or_b32 v117, v117, s20, v113
	global_store_dwordx2 v[106:107], v[116:117], off offset:1536 nt
	v_mul_f32_e32 v113, v83, v83
	v_mul_f32_e32 v116, v85, v85
	v_fmac_f32_e32 v113, v82, v82
	v_fmac_f32_e32 v116, v84, v84
	v_add_f32_e32 v113, v113, v116
	v_add_f32_e32 v99, v113, v99
	v_mov_b32_e32 v113, v186
	v_pk_mul_f32 v[112:113], v[176:177], v[112:113] op_sel_hi:[0,1]
	v_pk_fma_f32 v[78:79], v[50:51], v[112:113], v[78:79]
	v_pk_mul_f32 v[114:115], v[176:177], v[114:115] op_sel_hi:[0,1]
	v_bfe_u32 v112, v78, 16, 1
	v_add3_u32 v112, v78, v112, s22
	v_bfe_u32 v113, v79, 16, 1
	v_pk_fma_f32 v[80:81], v[52:53], v[114:115], v[80:81]
	v_lshrrev_b32_e32 v112, 16, v112
	v_add3_u32 v113, v79, v113, s22
	v_and_or_b32 v112, v113, s20, v112
	v_bfe_u32 v113, v80, 16, 1
	v_add3_u32 v113, v80, v113, s22
	v_bfe_u32 v114, v81, 16, 1
	v_lshrrev_b32_e32 v113, 16, v113
	v_add3_u32 v114, v81, v114, s22
	v_and_or_b32 v113, v114, s20, v113
	global_store_dwordx2 v[106:107], v[112:113], off offset:2048 nt
	v_mul_f32_e32 v112, v79, v79
	v_mul_f32_e32 v113, v81, v81
	v_fmac_f32_e32 v112, v78, v78
	v_fmac_f32_e32 v113, v80, v80
	v_add_f32_e32 v112, v112, v113
	v_add_f32_e32 v99, v112, v99
	v_mov_b32_e32 v112, v110
	v_mov_b32_e32 v113, v108
	v_pk_mul_f32 v[112:113], v[176:177], v[112:113] op_sel_hi:[0,1]
	v_mov_b32_e32 v108, v111
	v_pk_mul_f32 v[108:109], v[176:177], v[108:109] op_sel_hi:[0,1]
	v_pk_fma_f32 v[74:75], v[42:43], v[112:113], v[74:75]
	v_pk_mul_f32 v[102:103], v[176:177], v[102:103] op_sel_hi:[0,1]
	v_pk_fma_f32 v[76:77], v[44:45], v[108:109], v[76:77]
	v_bfe_u32 v108, v74, 16, 1
	v_pk_fma_f32 v[70:71], v[38:39], v[102:103], v[70:71]
	v_add3_u32 v108, v74, v108, s22
	v_bfe_u32 v109, v75, 16, 1
	v_bfe_u32 v102, v70, 16, 1
	v_lshrrev_b32_e32 v108, 16, v108
	v_add3_u32 v109, v75, v109, s22
	v_pk_mul_f32 v[104:105], v[176:177], v[104:105] op_sel_hi:[0,1]
	v_add3_u32 v102, v70, v102, s22
	v_bfe_u32 v103, v71, 16, 1
	v_and_or_b32 v108, v109, s20, v108
	v_bfe_u32 v109, v76, 16, 1
	v_pk_fma_f32 v[72:73], v[40:41], v[104:105], v[72:73]
	v_lshrrev_b32_e32 v102, 16, v102
	v_add3_u32 v103, v71, v103, s22
	v_add3_u32 v109, v76, v109, s22
	v_bfe_u32 v110, v77, 16, 1
	v_and_or_b32 v102, v103, s20, v102
	v_bfe_u32 v103, v72, 16, 1
	v_lshrrev_b32_e32 v109, 16, v109
	v_add3_u32 v110, v77, v110, s22
	v_add3_u32 v103, v72, v103, s22
	v_bfe_u32 v104, v73, 16, 1
	v_and_or_b32 v109, v110, s20, v109
	v_lshrrev_b32_e32 v103, 16, v103
	v_add3_u32 v104, v73, v104, s22
	global_store_dwordx2 v[106:107], v[108:109], off offset:2560 nt
	v_mul_f32_e32 v108, v75, v75
	v_mul_f32_e32 v109, v77, v77
	v_and_or_b32 v103, v104, s20, v103
	v_fmac_f32_e32 v108, v74, v74
	v_fmac_f32_e32 v109, v76, v76
	global_store_dwordx2 v[106:107], v[102:103], off offset:3072 nt
	v_mul_f32_e32 v102, v71, v71
	v_mul_f32_e32 v103, v73, v73
	v_add_f32_e32 v108, v108, v109
	v_fmac_f32_e32 v102, v70, v70
	v_fmac_f32_e32 v103, v72, v72
	v_add_f32_e32 v99, v108, v99
	v_add_f32_e32 v102, v102, v103
	v_add_f32_e32 v102, v102, v99
	v_mov_b32_e32 v99, v187
	v_pk_mul_f32 v[98:99], v[176:177], v[98:99] op_sel_hi:[0,1]
	v_pk_fma_f32 v[66:67], v[34:35], v[98:99], v[66:67]
	v_pk_mul_f32 v[100:101], v[176:177], v[100:101] op_sel_hi:[0,1]
	v_bfe_u32 v98, v66, 16, 1
	v_add3_u32 v98, v66, v98, s22
	v_bfe_u32 v99, v67, 16, 1
	v_pk_fma_f32 v[68:69], v[36:37], v[100:101], v[68:69]
	v_lshrrev_b32_e32 v98, 16, v98
	v_add3_u32 v99, v67, v99, s22
	v_and_or_b32 v98, v99, s20, v98
	v_bfe_u32 v99, v68, 16, 1
	v_add3_u32 v99, v68, v99, s22
	v_bfe_u32 v100, v69, 16, 1
	v_lshrrev_b32_e32 v99, 16, v99
	v_add3_u32 v100, v69, v100, s22
	v_and_or_b32 v99, v100, s20, v99
	global_store_dwordx2 v[106:107], v[178:179], off nt
	global_store_dwordx2 v[106:107], v[98:99], off offset:3584 nt
	ds_read_b128 v[98:101], v253
	v_mul_f32_e32 v103, v67, v67
	v_mul_f32_e32 v104, v69, v69
	v_fmac_f32_e32 v103, v66, v66
	v_fmac_f32_e32 v104, v68, v68
	v_add_f32_e32 v103, v103, v104
	v_add_f32_e32 v102, v103, v102
	ds_bpermute_b32 v103, v1, v102
	s_waitcnt lgkmcnt(0)
	v_add_f32_e32 v102, v102, v103
	ds_bpermute_b32 v103, v206, v102
	s_waitcnt lgkmcnt(0)
	v_add_f32_e32 v102, v102, v103
	ds_bpermute_b32 v103, v207, v102
	s_waitcnt lgkmcnt(0)
	v_add_f32_e32 v102, v102, v103
	ds_bpermute_b32 v103, v208, v102
	s_waitcnt lgkmcnt(0)
	v_add_f32_e32 v102, v102, v103
	ds_bpermute_b32 v103, v209, v102
	s_waitcnt lgkmcnt(0)
	v_add_f32_e32 v102, v102, v103
	ds_bpermute_b32 v103, v210, v102
	s_waitcnt lgkmcnt(0)
	v_add_f32_e32 v102, v102, v103
	v_fmamk_f32 v102, v102, 0x3a000000, v211
	v_mul_f32_e32 v103, 0x4f800000, v102
	v_cmp_gt_f32_e32 vcc, s21, v102
	s_nop 1
	v_cndmask_b32_e32 v102, v102, v103, vcc
	v_sqrt_f32_e32 v103, v102
	s_nop 0
	v_add_u32_e32 v104, -1, v103
	v_fma_f32 v105, -v104, v103, v102
	v_cmp_ge_f32_e64 s[0:1], 0, v105
	v_add_u32_e32 v105, 1, v103
	s_nop 0
	v_cndmask_b32_e64 v104, v103, v104, s[0:1]
	v_fma_f32 v103, -v105, v103, v102
	v_cmp_lt_f32_e64 s[0:1], 0, v103
	s_nop 1
	v_cndmask_b32_e64 v103, v104, v105, s[0:1]
	v_mul_f32_e32 v104, 0x37800000, v103
	v_cndmask_b32_e32 v103, v103, v104, vcc
	v_cmp_class_f32_e32 vcc, v102, v212
	s_nop 1
	v_cndmask_b32_e32 v104, v103, v102, vcc
	v_div_scale_f32 v105, s[0:1], v104, v104, 1.0
	v_rcp_f32_e32 v106, v105
	v_lshl_add_u64 v[102:103], v[156:157], 0, s[12:13]
	v_fma_f32 v107, -v105, v106, 1.0
	v_fmac_f32_e32 v106, v107, v106
	v_div_scale_f32 v107, vcc, 1.0, v104, 1.0
	v_mul_f32_e32 v108, v107, v106
	v_fma_f32 v109, -v105, v108, v107
	v_fmac_f32_e32 v108, v109, v106
	v_fma_f32 v105, -v105, v108, v107
	v_div_fmas_f32 v105, v105, v106, v108
	v_div_fixup_f32 v104, v105, v104, 1.0
	v_mul_f32_e32 v94, v94, v104
	s_waitcnt lgkmcnt(0)
	v_mul_f32_e32 v94, v98, v94
	v_mul_f32_e32 v95, v95, v104
	v_mul_f32_e32 v95, v99, v95
	v_bfe_u32 v98, v94, 16, 1
	v_add3_u32 v94, v94, v98, s22
	v_bfe_u32 v98, v95, 16, 1
	v_lshrrev_b32_e32 v94, 16, v94
	v_add3_u32 v95, v95, v98, s22
	v_and_or_b32 v94, v95, s20, v94
	v_mul_f32_e32 v95, v96, v104
	v_mul_f32_e32 v95, v100, v95
	v_mul_f32_e32 v96, v97, v104
	v_mul_f32_e32 v96, v101, v96
	v_bfe_u32 v97, v95, 16, 1
	v_add3_u32 v95, v95, v97, s22
	v_bfe_u32 v97, v96, 16, 1
	v_lshrrev_b32_e32 v95, 16, v95
	v_add3_u32 v96, v96, v97, s22
	v_and_or_b32 v95, v96, s20, v95
	global_store_dwordx2 v[102:103], v[94:95], off
	ds_read_b128 v[94:97], v253 offset:1024
	v_mul_f32_e32 v90, v90, v104
	v_mul_f32_e32 v91, v91, v104
	v_mul_f32_e32 v86, v86, v104
	v_mul_f32_e32 v87, v87, v104
	v_mul_f32_e32 v82, v82, v104
	v_mul_f32_e32 v83, v83, v104
	v_mul_f32_e32 v78, v78, v104
	v_mul_f32_e32 v80, v80, v104
	v_mul_f32_e32 v79, v79, v104
	v_mul_f32_e32 v81, v81, v104
	v_mul_f32_e32 v74, v74, v104
	v_mul_f32_e32 v76, v76, v104
	v_mul_f32_e32 v75, v75, v104
	v_mul_f32_e32 v77, v77, v104
	v_mul_f32_e32 v70, v70, v104
	v_mul_f32_e32 v72, v72, v104
	v_mul_f32_e32 v71, v71, v104
	v_mul_f32_e32 v73, v73, v104
	v_mul_f32_e32 v66, v66, v104
	v_mul_f32_e32 v68, v68, v104
	v_mul_f32_e32 v67, v67, v104
	v_mul_f32_e32 v69, v69, v104
	s_waitcnt lgkmcnt(0)
	v_mul_f32_e32 v90, v94, v90
	v_mul_f32_e32 v91, v95, v91
	v_bfe_u32 v94, v90, 16, 1
	v_add3_u32 v90, v90, v94, s22
	v_bfe_u32 v94, v91, 16, 1
	v_lshrrev_b32_e32 v90, 16, v90
	v_add3_u32 v91, v91, v94, s22
	v_and_or_b32 v90, v91, s20, v90
	v_mul_f32_e32 v91, v92, v104
	v_mul_f32_e32 v91, v96, v91
	v_mul_f32_e32 v92, v93, v104
	v_mul_f32_e32 v92, v97, v92
	v_bfe_u32 v93, v91, 16, 1
	v_add3_u32 v91, v91, v93, s22
	v_bfe_u32 v93, v92, 16, 1
	v_lshrrev_b32_e32 v91, 16, v91
	v_add3_u32 v92, v92, v93, s22
	v_and_or_b32 v91, v92, s20, v91
	global_store_dwordx2 v[102:103], v[90:91], off offset:512
	ds_read_b128 v[90:93], v253 offset:2048
	s_waitcnt lgkmcnt(0)
	v_mul_f32_e32 v86, v90, v86
	v_mul_f32_e32 v87, v91, v87
	v_bfe_u32 v90, v86, 16, 1
	v_add3_u32 v86, v86, v90, s22
	v_bfe_u32 v90, v87, 16, 1
	v_lshrrev_b32_e32 v86, 16, v86
	v_add3_u32 v87, v87, v90, s22
	v_and_or_b32 v86, v87, s20, v86
	v_mul_f32_e32 v87, v88, v104
	v_mul_f32_e32 v87, v92, v87
	v_mul_f32_e32 v88, v89, v104
	v_mul_f32_e32 v88, v93, v88
	v_bfe_u32 v89, v87, 16, 1
	v_add3_u32 v87, v87, v89, s22
	v_bfe_u32 v89, v88, 16, 1
	v_lshrrev_b32_e32 v87, 16, v87
	v_add3_u32 v88, v88, v89, s22
	v_and_or_b32 v87, v88, s20, v87
	global_store_dwordx2 v[102:103], v[86:87], off offset:1024
	ds_read_b128 v[86:89], v253 offset:3072
	s_waitcnt lgkmcnt(0)
	v_mul_f32_e32 v82, v86, v82
	v_mul_f32_e32 v83, v87, v83
	v_bfe_u32 v86, v82, 16, 1
	v_add3_u32 v82, v82, v86, s22
	v_bfe_u32 v86, v83, 16, 1
	v_lshrrev_b32_e32 v82, 16, v82
	v_add3_u32 v83, v83, v86, s22
	v_and_or_b32 v82, v83, s20, v82
	v_mul_f32_e32 v83, v84, v104
	v_mul_f32_e32 v83, v88, v83
	v_mul_f32_e32 v84, v85, v104
	v_mul_f32_e32 v84, v89, v84
	v_bfe_u32 v85, v83, 16, 1
	v_add3_u32 v83, v83, v85, s22
	v_bfe_u32 v85, v84, 16, 1
	v_lshrrev_b32_e32 v83, 16, v83
	v_add3_u32 v84, v84, v85, s22
	v_and_or_b32 v83, v84, s20, v83
	global_store_dwordx2 v[102:103], v[82:83], off offset:1536
	ds_read_b128 v[82:85], v253 offset:4096
	s_waitcnt lgkmcnt(0)
	v_mul_f32_e32 v78, v82, v78
	v_mul_f32_e32 v80, v84, v80
	v_mul_f32_e32 v79, v83, v79
	v_mul_f32_e32 v81, v85, v81
	v_bfe_u32 v82, v78, 16, 1
	v_bfe_u32 v84, v80, 16, 1
	v_bfe_u32 v83, v79, 16, 1
	v_bfe_u32 v85, v81, 16, 1
	v_add3_u32 v78, v78, v82, s22
	v_add3_u32 v80, v80, v84, s22
	v_add3_u32 v79, v79, v83, s22
	v_add3_u32 v81, v81, v85, s22
	v_lshrrev_b32_e32 v78, 16, v78
	v_lshrrev_b32_e32 v80, 16, v80
	v_and_or_b32 v78, v79, s20, v78
	v_and_or_b32 v79, v81, s20, v80
	global_store_dwordx2 v[102:103], v[78:79], off offset:2048
	ds_read_b128 v[78:81], v253 offset:5120
	s_waitcnt lgkmcnt(0)
	v_mul_f32_e32 v74, v78, v74
	v_mul_f32_e32 v76, v80, v76
	v_mul_f32_e32 v75, v79, v75
	v_mul_f32_e32 v77, v81, v77
	v_bfe_u32 v78, v74, 16, 1
	v_bfe_u32 v80, v76, 16, 1
	v_bfe_u32 v79, v75, 16, 1
	v_bfe_u32 v81, v77, 16, 1
	v_add3_u32 v74, v74, v78, s22
	v_add3_u32 v76, v76, v80, s22
	v_add3_u32 v75, v75, v79, s22
	v_add3_u32 v77, v77, v81, s22
	v_lshrrev_b32_e32 v74, 16, v74
	v_lshrrev_b32_e32 v76, 16, v76
	v_and_or_b32 v74, v75, s20, v74
	v_and_or_b32 v75, v77, s20, v76
	global_store_dwordx2 v[102:103], v[74:75], off offset:2560
	ds_read_b128 v[74:77], v253 offset:6144
	s_waitcnt lgkmcnt(0)
	v_mul_f32_e32 v70, v74, v70
	v_mul_f32_e32 v72, v76, v72
	v_mul_f32_e32 v71, v75, v71
	v_mul_f32_e32 v73, v77, v73
	v_bfe_u32 v74, v70, 16, 1
	v_bfe_u32 v76, v72, 16, 1
	v_bfe_u32 v75, v71, 16, 1
	v_bfe_u32 v77, v73, 16, 1
	v_add3_u32 v70, v70, v74, s22
	v_add3_u32 v72, v72, v76, s22
	v_add3_u32 v71, v71, v75, s22
	v_add3_u32 v73, v73, v77, s22
	v_lshrrev_b32_e32 v70, 16, v70
	v_lshrrev_b32_e32 v72, 16, v72
	v_and_or_b32 v70, v71, s20, v70
	v_and_or_b32 v71, v73, s20, v72
	global_store_dwordx2 v[102:103], v[70:71], off offset:3072
	ds_read_b128 v[70:73], v253 offset:7168
	s_waitcnt lgkmcnt(0)
	v_mul_f32_e32 v66, v70, v66
	v_mul_f32_e32 v68, v72, v68
	v_mul_f32_e32 v67, v71, v67
	v_mul_f32_e32 v69, v73, v69
	v_bfe_u32 v70, v66, 16, 1
	v_bfe_u32 v72, v68, 16, 1
	v_bfe_u32 v71, v67, 16, 1
	v_bfe_u32 v73, v69, 16, 1
	v_add3_u32 v66, v66, v70, s22
	v_add3_u32 v68, v68, v72, s22
	v_add3_u32 v67, v67, v71, s22
	v_add3_u32 v69, v69, v73, s22
	v_lshrrev_b32_e32 v66, 16, v66
	v_lshrrev_b32_e32 v68, 16, v68
	v_and_or_b32 v66, v67, s20, v66
	v_and_or_b32 v67, v69, s20, v68
	global_store_dwordx2 v[102:103], v[66:67], off offset:3584
.LBB0_1065:
	s_andn2_b64 vcc, exec, s[10:11]
	s_cbranch_vccnz .LBB0_1058
	v_and_b32_e32 v83, 0xffff0000, v172
	v_and_b32_e32 v85, 0xffff0000, v173
	v_lshlrev_b32_e32 v82, 16, v172
	v_lshlrev_b32_e32 v84, 16, v173
	v_mul_f32_e32 v66, v85, v85
	v_and_b32_e32 v89, 0xffff0000, v175
	v_and_b32_e32 v88, 0xffff0000, v174
	v_mul_f32_e32 v70, v83, v83
	v_pk_fma_f32 v[66:67], v[84:85], v[84:85], v[66:67] op_sel_hi:[1,1,0]
	v_lshlrev_b32_e32 v87, 16, v175
	v_lshlrev_b32_e32 v86, 16, v174
	v_pk_mul_f32 v[68:69], v[88:89], v[88:89]
	v_lshlrev_b32_e32 v95, 16, v164
	v_pk_fma_f32 v[70:71], v[82:83], v[82:83], v[70:71] op_sel_hi:[1,1,0]
	v_pk_fma_f32 v[68:69], v[86:87], v[86:87], v[68:69]
	v_and_b32_e32 v97, 0xffff0000, v164
	v_mov_b32_e32 v94, v70
	v_mov_b32_e32 v72, v66
	v_mov_b32_e32 v73, v95
	v_mul_f32_e32 v74, v97, v97
	v_pk_add_f32 v[66:67], v[70:71], v[66:67]
	v_pk_mul_f32 v[70:71], v[94:95], v[72:73]
	v_pk_add_f32 v[68:69], v[68:69], v[68:69] op_sel:[0,1] op_sel_hi:[1,0]
	v_and_b32_e32 v91, 0xffff0000, v166
	v_and_b32_e32 v93, 0xffff0000, v167
	v_mov_b32_e32 v67, v71
	v_mov_b32_e32 v69, v74
	v_lshlrev_b32_e32 v90, 16, v166
	v_lshlrev_b32_e32 v92, 16, v167
	v_lshlrev_b32_e32 v98, 16, v165
	v_and_b32_e32 v99, 0xffff0000, v165
	v_pk_add_f32 v[66:67], v[66:67], v[68:69]
	v_mul_f32_e32 v68, v91, v91
	v_mul_f32_e32 v70, v93, v93
	v_mul_f32_e32 v75, v98, v98
	v_mul_f32_e32 v76, v99, v99
	v_pk_fma_f32 v[68:69], v[90:91], v[90:91], v[68:69] op_sel_hi:[1,1,0]
	v_pk_fma_f32 v[70:71], v[92:93], v[92:93], v[70:71] op_sel_hi:[1,1,0]
	v_mov_b32_e32 v69, v75
	v_mov_b32_e32 v71, v76
	v_pk_add_f32 v[68:69], v[68:69], v[70:71]
	v_and_b32_e32 v103, 0xffff0000, v171
	v_and_b32_e32 v102, 0xffff0000, v170
	v_pk_add_f32 v[76:77], v[66:67], v[68:69]
	v_lshlrev_b32_e32 v101, 16, v171
	v_lshlrev_b32_e32 v100, 16, v170
	v_pk_mul_f32 v[66:67], v[102:103], v[102:103]
	v_and_b32_e32 v79, 0xffff0000, v169
	v_pk_fma_f32 v[66:67], v[100:101], v[100:101], v[66:67]
	v_and_b32_e32 v78, 0xffff0000, v168
	v_pk_add_f32 v[104:105], v[66:67], v[66:67] op_sel:[0,1] op_sel_hi:[1,0]
	v_lshlrev_b32_e32 v71, 16, v160
	v_pk_add_f32 v[76:77], v[76:77], v[76:77] op_sel:[0,1] op_sel_hi:[1,0]
	v_lshlrev_b32_e32 v81, 16, v169
	v_lshlrev_b32_e32 v80, 16, v168
	v_pk_mul_f32 v[66:67], v[78:79], v[78:79]
	v_mov_b32_e32 v70, v76
	v_mov_b32_e32 v108, v104
	v_mov_b32_e32 v109, v71
	v_pk_fma_f32 v[106:107], v[80:81], v[80:81], v[66:67]
	v_and_b32_e32 v69, 0xffff0000, v160
	v_pk_add_f32 v[76:77], v[76:77], v[104:105]
	v_pk_mul_f32 v[104:105], v[70:71], v[108:109]
	v_and_b32_e32 v73, 0xffff0000, v162
	v_mul_f32_e32 v68, v69, v69
	v_mov_b32_e32 v77, v105
	v_pk_add_f32 v[104:105], v[106:107], v[106:107] op_sel:[0,1] op_sel_hi:[1,0]
	v_lshlrev_b32_e32 v72, 16, v162
	v_and_b32_e32 v75, 0xffff0000, v163
	v_mov_b32_e32 v105, v68
	v_mul_f32_e32 v68, v73, v73
	v_lshlrev_b32_e32 v74, 16, v163
	v_lshlrev_b32_e32 v66, 16, v161
	v_and_b32_e32 v67, 0xffff0000, v161
	v_pk_add_f32 v[76:77], v[76:77], v[104:105]
	v_pk_fma_f32 v[104:105], v[72:73], v[72:73], v[68:69] op_sel_hi:[1,1,0]
	v_mul_f32_e32 v68, v75, v75
	v_mul_f32_e32 v94, v66, v66
	v_mul_f32_e32 v96, v67, v67
	v_pk_fma_f32 v[106:107], v[74:75], v[74:75], v[68:69] op_sel_hi:[1,1,0]
	v_mov_b32_e32 v105, v94
	v_mov_b32_e32 v107, v96
	v_pk_add_f32 v[104:105], v[104:105], v[106:107]
	s_ashr_i32 s7, s6, 31
	v_pk_add_f32 v[76:77], v[76:77], v[104:105]
	s_lshl_b64 s[6:7], s[6:7], 12
	v_add_f32_e32 v68, v76, v77
	ds_bpermute_b32 v70, v1, v68
	s_waitcnt lgkmcnt(0)
	v_add_f32_e32 v68, v68, v70
	ds_bpermute_b32 v70, v206, v68
	s_waitcnt lgkmcnt(0)
	v_add_f32_e32 v68, v68, v70
	ds_bpermute_b32 v70, v207, v68
	s_waitcnt lgkmcnt(0)
	v_add_f32_e32 v68, v68, v70
	ds_bpermute_b32 v70, v208, v68
	s_waitcnt lgkmcnt(0)
	v_add_f32_e32 v68, v68, v70
	ds_bpermute_b32 v70, v209, v68
	s_waitcnt lgkmcnt(0)
	v_add_f32_e32 v68, v68, v70
	ds_bpermute_b32 v70, v210, v68
	s_waitcnt lgkmcnt(0)
	v_add_f32_e32 v68, v68, v70
	v_fmamk_f32 v68, v68, 0x3a000000, v211
	v_mul_f32_e32 v70, 0x4f800000, v68
	v_cmp_gt_f32_e32 vcc, s21, v68
	s_nop 1
	v_cndmask_b32_e32 v68, v68, v70, vcc
	v_sqrt_f32_e32 v70, v68
	s_nop 0
	v_add_u32_e32 v76, -1, v70
	v_fma_f32 v77, -v76, v70, v68
	v_cmp_ge_f32_e64 s[0:1], 0, v77
	v_add_u32_e32 v77, 1, v70
	s_nop 0
	v_cndmask_b32_e64 v76, v70, v76, s[0:1]
	v_fma_f32 v70, -v77, v70, v68
	v_cmp_lt_f32_e64 s[0:1], 0, v70
	s_nop 1
	v_cndmask_b32_e64 v70, v76, v77, s[0:1]
	v_mul_f32_e32 v76, 0x37800000, v70
	v_cndmask_b32_e32 v70, v70, v76, vcc
	v_cmp_class_f32_e32 vcc, v68, v212
	v_lshl_add_u64 v[76:77], v[154:155], 0, s[6:7]
	s_nop 0
	v_cndmask_b32_e32 v68, v70, v68, vcc
	v_div_scale_f32 v70, s[0:1], v68, v68, 1.0
	v_rcp_f32_e32 v94, v70
	s_nop 0
	v_fma_f32 v96, -v70, v94, 1.0
	v_fmac_f32_e32 v94, v96, v94
	v_div_scale_f32 v96, vcc, 1.0, v68, 1.0
	v_mul_f32_e32 v104, v96, v94
	v_fma_f32 v105, -v70, v104, v96
	v_fmac_f32_e32 v104, v105, v94
	v_fma_f32 v70, -v70, v104, v96
	v_div_fmas_f32 v70, v70, v94, v104
	v_div_fixup_f32 v70, v70, v68, 1.0
	v_pk_mul_f32 v[82:83], v[70:71], v[82:83] op_sel_hi:[0,1]
	v_pk_fma_f32 v[30:31], v[46:47], v[82:83], v[30:31]
	v_pk_mul_f32 v[84:85], v[70:71], v[84:85] op_sel_hi:[0,1]
	v_bfe_u32 v46, v30, 16, 1
	v_add3_u32 v46, v30, v46, s22
	v_bfe_u32 v47, v31, 16, 1
	v_pk_fma_f32 v[32:33], v[48:49], v[84:85], v[32:33]
	v_lshrrev_b32_e32 v46, 16, v46
	v_add3_u32 v47, v31, v47, s22
	v_and_or_b32 v46, v47, s20, v46
	v_bfe_u32 v47, v32, 16, 1
	v_add3_u32 v47, v32, v47, s22
	v_bfe_u32 v48, v33, 16, 1
	v_lshrrev_b32_e32 v47, 16, v47
	v_add3_u32 v48, v33, v48, s22
	v_and_or_b32 v47, v48, s20, v47
	global_store_dwordx2 v[76:77], v[46:47], off nt
	v_mul_f32_e32 v46, v31, v31
	v_mul_f32_e32 v47, v33, v33
	v_fmac_f32_e32 v46, v30, v30
	v_fmac_f32_e32 v47, v32, v32
	v_add_f32_e32 v68, v46, v47
	v_mov_b32_e32 v46, v86
	v_mov_b32_e32 v47, v88
	v_pk_mul_f32 v[46:47], v[70:71], v[46:47] op_sel_hi:[0,1]
	v_pk_fma_f32 v[26:27], v[62:63], v[46:47], v[26:27]
	v_mov_b32_e32 v88, v87
	v_bfe_u32 v46, v26, 16, 1
	v_pk_mul_f32 v[48:49], v[70:71], v[88:89] op_sel_hi:[0,1]
	v_add3_u32 v46, v26, v46, s22
	v_bfe_u32 v47, v27, 16, 1
	v_pk_fma_f32 v[28:29], v[64:65], v[48:49], v[28:29]
	v_lshrrev_b32_e32 v46, 16, v46
	v_add3_u32 v47, v27, v47, s22
	v_and_or_b32 v46, v47, s20, v46
	v_bfe_u32 v47, v28, 16, 1
	v_add3_u32 v47, v28, v47, s22
	v_bfe_u32 v48, v29, 16, 1
	v_lshrrev_b32_e32 v47, 16, v47
	v_add3_u32 v48, v29, v48, s22
	v_and_or_b32 v47, v48, s20, v47
	global_store_dwordx2 v[76:77], v[46:47], off offset:512 nt
	v_mul_f32_e32 v46, v27, v27
	v_mul_f32_e32 v47, v29, v29
	v_fmac_f32_e32 v46, v26, v26
	v_fmac_f32_e32 v47, v28, v28
	v_add_f32_e32 v46, v46, v47
	v_add_f32_e32 v62, v68, v46
	v_pk_mul_f32 v[46:47], v[70:71], v[90:91] op_sel_hi:[0,1]
	v_pk_fma_f32 v[22:23], v[58:59], v[46:47], v[22:23]
	v_pk_mul_f32 v[48:49], v[70:71], v[92:93] op_sel_hi:[0,1]
	v_bfe_u32 v46, v22, 16, 1
	v_add3_u32 v46, v22, v46, s22
	v_bfe_u32 v47, v23, 16, 1
	v_pk_fma_f32 v[24:25], v[60:61], v[48:49], v[24:25]
	v_lshrrev_b32_e32 v46, 16, v46
	v_add3_u32 v47, v23, v47, s22
	v_and_or_b32 v46, v47, s20, v46
	v_bfe_u32 v47, v24, 16, 1
	v_add3_u32 v47, v24, v47, s22
	v_bfe_u32 v48, v25, 16, 1
	v_lshrrev_b32_e32 v47, 16, v47
	v_add3_u32 v48, v25, v48, s22
	v_and_or_b32 v47, v48, s20, v47
	global_store_dwordx2 v[76:77], v[46:47], off offset:1024 nt
	v_mul_f32_e32 v46, v23, v23
	v_mul_f32_e32 v47, v25, v25
	v_fmac_f32_e32 v46, v22, v22
	v_fmac_f32_e32 v47, v24, v24
	v_add_f32_e32 v46, v46, v47
	v_mov_b32_e32 v96, v95
	v_add_f32_e32 v58, v46, v62
	v_pk_mul_f32 v[46:47], v[70:71], v[96:97] op_sel_hi:[0,1]
	v_pk_fma_f32 v[18:19], v[54:55], v[46:47], v[18:19]
	v_pk_mul_f32 v[48:49], v[70:71], v[98:99] op_sel_hi:[0,1]
	v_bfe_u32 v46, v18, 16, 1
	v_add3_u32 v46, v18, v46, s22
	v_bfe_u32 v47, v19, 16, 1
	v_pk_fma_f32 v[20:21], v[56:57], v[48:49], v[20:21]
	v_lshrrev_b32_e32 v46, 16, v46
	v_add3_u32 v47, v19, v47, s22
	v_and_or_b32 v46, v47, s20, v46
	v_bfe_u32 v47, v20, 16, 1
	v_add3_u32 v47, v20, v47, s22
	v_bfe_u32 v48, v21, 16, 1
	v_lshrrev_b32_e32 v47, 16, v47
	v_add3_u32 v48, v21, v48, s22
	v_and_or_b32 v47, v48, s20, v47
	global_store_dwordx2 v[76:77], v[46:47], off offset:1536 nt
	v_mul_f32_e32 v46, v19, v19
	v_mul_f32_e32 v47, v21, v21
	v_fmac_f32_e32 v46, v18, v18
	v_fmac_f32_e32 v47, v20, v20
	v_add_f32_e32 v46, v46, v47
	v_add_f32_e32 v54, v46, v58
	v_mov_b32_e32 v46, v100
	v_mov_b32_e32 v47, v102
	v_pk_mul_f32 v[46:47], v[70:71], v[46:47] op_sel_hi:[0,1]
	v_pk_fma_f32 v[14:15], v[50:51], v[46:47], v[14:15]
	v_mov_b32_e32 v102, v101
	v_bfe_u32 v46, v14, 16, 1
	v_pk_mul_f32 v[48:49], v[70:71], v[102:103] op_sel_hi:[0,1]
	v_add3_u32 v46, v14, v46, s22
	v_bfe_u32 v47, v15, 16, 1
	v_pk_fma_f32 v[16:17], v[52:53], v[48:49], v[16:17]
	v_lshrrev_b32_e32 v46, 16, v46
	v_add3_u32 v47, v15, v47, s22
	v_and_or_b32 v46, v47, s20, v46
	v_bfe_u32 v47, v16, 16, 1
	v_add3_u32 v47, v16, v47, s22
	v_bfe_u32 v48, v17, 16, 1
	v_lshrrev_b32_e32 v47, 16, v47
	v_add3_u32 v48, v17, v48, s22
	v_and_or_b32 v47, v48, s20, v47
	global_store_dwordx2 v[76:77], v[46:47], off offset:2048 nt
	v_mul_f32_e32 v46, v15, v15
	v_mul_f32_e32 v47, v17, v17
	v_fmac_f32_e32 v46, v14, v14
	v_fmac_f32_e32 v47, v16, v16
	v_add_f32_e32 v46, v46, v47
	v_add_f32_e32 v50, v46, v54
	v_mov_b32_e32 v46, v80
	v_mov_b32_e32 v47, v78
	v_pk_mul_f32 v[46:47], v[70:71], v[46:47] op_sel_hi:[0,1]
	v_pk_fma_f32 v[10:11], v[42:43], v[46:47], v[10:11]
	v_mov_b32_e32 v78, v81
	v_bfe_u32 v42, v10, 16, 1
	v_pk_mul_f32 v[48:49], v[70:71], v[78:79] op_sel_hi:[0,1]
	v_add3_u32 v42, v10, v42, s22
	v_bfe_u32 v43, v11, 16, 1
	v_pk_fma_f32 v[12:13], v[44:45], v[48:49], v[12:13]
	v_lshrrev_b32_e32 v42, 16, v42
	v_add3_u32 v43, v11, v43, s22
	v_and_or_b32 v42, v43, s20, v42
	v_bfe_u32 v43, v12, 16, 1
	v_add3_u32 v43, v12, v43, s22
	v_bfe_u32 v44, v13, 16, 1
	v_lshrrev_b32_e32 v43, 16, v43
	v_add3_u32 v44, v13, v44, s22
	v_and_or_b32 v43, v44, s20, v43
	global_store_dwordx2 v[76:77], v[42:43], off offset:2560 nt
	v_mul_f32_e32 v42, v11, v11
	v_mul_f32_e32 v43, v13, v13
	v_fmac_f32_e32 v42, v10, v10
	v_fmac_f32_e32 v43, v12, v12
	v_add_f32_e32 v42, v42, v43
	v_add_f32_e32 v46, v42, v50
	v_pk_mul_f32 v[42:43], v[70:71], v[72:73] op_sel_hi:[0,1]
	v_pk_fma_f32 v[6:7], v[38:39], v[42:43], v[6:7]
	v_pk_mul_f32 v[44:45], v[70:71], v[74:75] op_sel_hi:[0,1]
	v_bfe_u32 v38, v6, 16, 1
	v_add3_u32 v38, v6, v38, s22
	v_bfe_u32 v39, v7, 16, 1
	v_pk_fma_f32 v[8:9], v[40:41], v[44:45], v[8:9]
	v_lshrrev_b32_e32 v38, 16, v38
	v_add3_u32 v39, v7, v39, s22
	v_and_or_b32 v38, v39, s20, v38
	v_bfe_u32 v39, v8, 16, 1
	v_add3_u32 v39, v8, v39, s22
	v_bfe_u32 v40, v9, 16, 1
	v_lshrrev_b32_e32 v39, 16, v39
	v_add3_u32 v40, v9, v40, s22
	v_and_or_b32 v39, v40, s20, v39
	global_store_dwordx2 v[76:77], v[38:39], off offset:3072 nt
	v_mul_f32_e32 v38, v7, v7
	v_mul_f32_e32 v39, v9, v9
	v_fmac_f32_e32 v38, v6, v6
	v_fmac_f32_e32 v39, v8, v8
	v_add_f32_e32 v38, v38, v39
	v_mov_b32_e32 v68, v71
	v_add_f32_e32 v42, v38, v46
	v_pk_mul_f32 v[38:39], v[70:71], v[68:69] op_sel_hi:[0,1]
	v_pk_fma_f32 v[2:3], v[34:35], v[38:39], v[2:3]
	v_pk_mul_f32 v[40:41], v[70:71], v[66:67] op_sel_hi:[0,1]
	v_bfe_u32 v34, v2, 16, 1
	v_add3_u32 v34, v2, v34, s22
	v_bfe_u32 v35, v3, 16, 1
	v_pk_fma_f32 v[4:5], v[36:37], v[40:41], v[4:5]
	v_lshrrev_b32_e32 v34, 16, v34
	v_add3_u32 v35, v3, v35, s22
	v_and_or_b32 v34, v35, s20, v34
	v_bfe_u32 v35, v4, 16, 1
	v_add3_u32 v35, v4, v35, s22
	v_bfe_u32 v36, v5, 16, 1
	v_lshrrev_b32_e32 v35, 16, v35
	v_add3_u32 v36, v5, v36, s22
	v_and_or_b32 v35, v36, s20, v35
	global_store_dwordx2 v[76:77], v[34:35], off offset:3584 nt
	ds_read_b128 v[34:37], v253
	v_mul_f32_e32 v38, v3, v3
	v_mul_f32_e32 v39, v5, v5
	v_fmac_f32_e32 v38, v2, v2
	v_fmac_f32_e32 v39, v4, v4
	v_add_f32_e32 v38, v38, v39
	v_add_f32_e32 v38, v38, v42
	ds_bpermute_b32 v39, v1, v38
	s_waitcnt lgkmcnt(0)
	v_add_f32_e32 v38, v38, v39
	ds_bpermute_b32 v39, v206, v38
	s_waitcnt lgkmcnt(0)
	v_add_f32_e32 v38, v38, v39
	ds_bpermute_b32 v39, v207, v38
	s_waitcnt lgkmcnt(0)
	v_add_f32_e32 v38, v38, v39
	ds_bpermute_b32 v39, v208, v38
	s_waitcnt lgkmcnt(0)
	v_add_f32_e32 v38, v38, v39
	ds_bpermute_b32 v39, v209, v38
	s_waitcnt lgkmcnt(0)
	v_add_f32_e32 v38, v38, v39
	ds_bpermute_b32 v39, v210, v38
	s_waitcnt lgkmcnt(0)
	v_add_f32_e32 v38, v38, v39
	v_fmamk_f32 v38, v38, 0x3a000000, v211
	v_mul_f32_e32 v39, 0x4f800000, v38
	v_cmp_gt_f32_e32 vcc, s21, v38
	s_nop 1
	v_cndmask_b32_e32 v38, v38, v39, vcc
	v_sqrt_f32_e32 v39, v38
	s_nop 0
	v_add_u32_e32 v40, -1, v39
	v_fma_f32 v41, -v40, v39, v38
	v_cmp_ge_f32_e64 s[0:1], 0, v41
	v_add_u32_e32 v41, 1, v39
	s_nop 0
	v_cndmask_b32_e64 v40, v39, v40, s[0:1]
	v_fma_f32 v39, -v41, v39, v38
	v_cmp_lt_f32_e64 s[0:1], 0, v39
	s_nop 1
	v_cndmask_b32_e64 v39, v40, v41, s[0:1]
	v_mul_f32_e32 v40, 0x37800000, v39
	v_cndmask_b32_e32 v39, v39, v40, vcc
	v_cmp_class_f32_e32 vcc, v38, v212
	s_nop 1
	v_cndmask_b32_e32 v40, v39, v38, vcc
	v_div_scale_f32 v41, s[0:1], v40, v40, 1.0
	v_rcp_f32_e32 v42, v41
	v_lshl_add_u64 v[38:39], v[156:157], 0, s[6:7]
	v_fma_f32 v43, -v41, v42, 1.0
	v_fmac_f32_e32 v42, v43, v42
	v_div_scale_f32 v43, vcc, 1.0, v40, 1.0
	v_mul_f32_e32 v44, v43, v42
	v_fma_f32 v45, -v41, v44, v43
	v_fmac_f32_e32 v44, v45, v42
	v_fma_f32 v41, -v41, v44, v43
	v_div_fmas_f32 v41, v41, v42, v44
	v_div_fixup_f32 v40, v41, v40, 1.0
	v_mul_f32_e32 v30, v30, v40
	s_waitcnt lgkmcnt(0)
	v_mul_f32_e32 v30, v34, v30
	v_mul_f32_e32 v31, v31, v40
	v_mul_f32_e32 v31, v35, v31
	v_bfe_u32 v34, v30, 16, 1
	v_add3_u32 v30, v30, v34, s22
	v_bfe_u32 v34, v31, 16, 1
	v_lshrrev_b32_e32 v30, 16, v30
	v_add3_u32 v31, v31, v34, s22
	v_and_or_b32 v30, v31, s20, v30
	v_mul_f32_e32 v31, v32, v40
	v_mul_f32_e32 v31, v36, v31
	v_mul_f32_e32 v32, v33, v40
	v_mul_f32_e32 v32, v37, v32
	v_bfe_u32 v33, v31, 16, 1
	v_add3_u32 v31, v31, v33, s22
	v_bfe_u32 v33, v32, 16, 1
	v_lshrrev_b32_e32 v31, 16, v31
	v_add3_u32 v32, v32, v33, s22
	v_and_or_b32 v31, v32, s20, v31
	global_store_dwordx2 v[38:39], v[30:31], off
	ds_read_b128 v[30:33], v253 offset:1024
	v_mul_f32_e32 v26, v26, v40
	v_mul_f32_e32 v27, v27, v40
	v_mul_f32_e32 v22, v22, v40
	v_mul_f32_e32 v23, v23, v40
	v_mul_f32_e32 v18, v18, v40
	v_mul_f32_e32 v19, v19, v40
	v_mul_f32_e32 v14, v14, v40
	v_mul_f32_e32 v16, v16, v40
	v_mul_f32_e32 v15, v15, v40
	v_mul_f32_e32 v17, v17, v40
	v_mul_f32_e32 v10, v10, v40
	v_mul_f32_e32 v12, v12, v40
	v_mul_f32_e32 v11, v11, v40
	v_mul_f32_e32 v13, v13, v40
	v_mul_f32_e32 v6, v6, v40
	v_mul_f32_e32 v8, v8, v40
	v_mul_f32_e32 v7, v7, v40
	v_mul_f32_e32 v9, v9, v40
	v_mul_f32_e32 v2, v2, v40
	v_mul_f32_e32 v4, v4, v40
	v_mul_f32_e32 v3, v3, v40
	v_mul_f32_e32 v5, v5, v40
	s_waitcnt lgkmcnt(0)
	v_mul_f32_e32 v26, v30, v26
	v_mul_f32_e32 v27, v31, v27
	v_bfe_u32 v30, v26, 16, 1
	v_add3_u32 v26, v26, v30, s22
	v_bfe_u32 v30, v27, 16, 1
	v_lshrrev_b32_e32 v26, 16, v26
	v_add3_u32 v27, v27, v30, s22
	v_and_or_b32 v26, v27, s20, v26
	v_mul_f32_e32 v27, v28, v40
	v_mul_f32_e32 v27, v32, v27
	v_mul_f32_e32 v28, v29, v40
	v_mul_f32_e32 v28, v33, v28
	v_bfe_u32 v29, v27, 16, 1
	v_add3_u32 v27, v27, v29, s22
	v_bfe_u32 v29, v28, 16, 1
	v_lshrrev_b32_e32 v27, 16, v27
	v_add3_u32 v28, v28, v29, s22
	v_and_or_b32 v27, v28, s20, v27
	global_store_dwordx2 v[38:39], v[26:27], off offset:512
	ds_read_b128 v[26:29], v253 offset:2048
	s_waitcnt lgkmcnt(0)
	v_mul_f32_e32 v22, v26, v22
	v_mul_f32_e32 v23, v27, v23
	v_bfe_u32 v26, v22, 16, 1
	v_add3_u32 v22, v22, v26, s22
	v_bfe_u32 v26, v23, 16, 1
	v_lshrrev_b32_e32 v22, 16, v22
	v_add3_u32 v23, v23, v26, s22
	v_and_or_b32 v22, v23, s20, v22
	v_mul_f32_e32 v23, v24, v40
	v_mul_f32_e32 v23, v28, v23
	v_mul_f32_e32 v24, v25, v40
	v_mul_f32_e32 v24, v29, v24
	v_bfe_u32 v25, v23, 16, 1
	v_add3_u32 v23, v23, v25, s22
	v_bfe_u32 v25, v24, 16, 1
	v_lshrrev_b32_e32 v23, 16, v23
	v_add3_u32 v24, v24, v25, s22
	v_and_or_b32 v23, v24, s20, v23
	global_store_dwordx2 v[38:39], v[22:23], off offset:1024
	ds_read_b128 v[22:25], v253 offset:3072
	s_waitcnt lgkmcnt(0)
	v_mul_f32_e32 v18, v22, v18
	v_mul_f32_e32 v19, v23, v19
	v_bfe_u32 v22, v18, 16, 1
	v_add3_u32 v18, v18, v22, s22
	v_bfe_u32 v22, v19, 16, 1
	v_lshrrev_b32_e32 v18, 16, v18
	v_add3_u32 v19, v19, v22, s22
	v_and_or_b32 v18, v19, s20, v18
	v_mul_f32_e32 v19, v20, v40
	v_mul_f32_e32 v19, v24, v19
	v_mul_f32_e32 v20, v21, v40
	v_mul_f32_e32 v20, v25, v20
	v_bfe_u32 v21, v19, 16, 1
	v_add3_u32 v19, v19, v21, s22
	v_bfe_u32 v21, v20, 16, 1
	v_lshrrev_b32_e32 v19, 16, v19
	v_add3_u32 v20, v20, v21, s22
	v_and_or_b32 v19, v20, s20, v19
	global_store_dwordx2 v[38:39], v[18:19], off offset:1536
	ds_read_b128 v[18:21], v253 offset:4096
	s_waitcnt lgkmcnt(0)
	v_mul_f32_e32 v14, v18, v14
	v_mul_f32_e32 v16, v20, v16
	v_mul_f32_e32 v15, v19, v15
	v_mul_f32_e32 v17, v21, v17
	v_bfe_u32 v18, v14, 16, 1
	v_bfe_u32 v20, v16, 16, 1
	v_bfe_u32 v19, v15, 16, 1
	v_bfe_u32 v21, v17, 16, 1
	v_add3_u32 v14, v14, v18, s22
	v_add3_u32 v16, v16, v20, s22
	v_add3_u32 v15, v15, v19, s22
	v_add3_u32 v17, v17, v21, s22
	v_lshrrev_b32_e32 v14, 16, v14
	v_lshrrev_b32_e32 v16, 16, v16
	v_and_or_b32 v14, v15, s20, v14
	v_and_or_b32 v15, v17, s20, v16
	global_store_dwordx2 v[38:39], v[14:15], off offset:2048
	ds_read_b128 v[14:17], v253 offset:5120
	s_waitcnt lgkmcnt(0)
	v_mul_f32_e32 v10, v14, v10
	v_mul_f32_e32 v12, v16, v12
	v_mul_f32_e32 v11, v15, v11
	v_mul_f32_e32 v13, v17, v13
	v_bfe_u32 v14, v10, 16, 1
	v_bfe_u32 v16, v12, 16, 1
	v_bfe_u32 v15, v11, 16, 1
	v_bfe_u32 v17, v13, 16, 1
	v_add3_u32 v10, v10, v14, s22
	v_add3_u32 v12, v12, v16, s22
	v_add3_u32 v11, v11, v15, s22
	v_add3_u32 v13, v13, v17, s22
	v_lshrrev_b32_e32 v10, 16, v10
	v_lshrrev_b32_e32 v12, 16, v12
	v_and_or_b32 v10, v11, s20, v10
	v_and_or_b32 v11, v13, s20, v12
	global_store_dwordx2 v[38:39], v[10:11], off offset:2560
	ds_read_b128 v[10:13], v253 offset:6144
	s_waitcnt lgkmcnt(0)
	v_mul_f32_e32 v6, v10, v6
	v_mul_f32_e32 v8, v12, v8
	v_mul_f32_e32 v7, v11, v7
	v_mul_f32_e32 v9, v13, v9
	v_bfe_u32 v10, v6, 16, 1
	v_bfe_u32 v12, v8, 16, 1
	v_bfe_u32 v11, v7, 16, 1
	v_bfe_u32 v13, v9, 16, 1
	v_add3_u32 v6, v6, v10, s22
	v_add3_u32 v8, v8, v12, s22
	v_add3_u32 v7, v7, v11, s22
	v_add3_u32 v9, v9, v13, s22
	v_lshrrev_b32_e32 v6, 16, v6
	v_lshrrev_b32_e32 v8, 16, v8
	v_and_or_b32 v6, v7, s20, v6
	v_and_or_b32 v7, v9, s20, v8
	global_store_dwordx2 v[38:39], v[6:7], off offset:3072
	ds_read_b128 v[6:9], v253 offset:7168
	s_waitcnt lgkmcnt(0)
	v_mul_f32_e32 v2, v6, v2
	v_mul_f32_e32 v4, v8, v4
	v_mul_f32_e32 v3, v7, v3
	v_mul_f32_e32 v5, v9, v5
	v_bfe_u32 v6, v2, 16, 1
	v_bfe_u32 v8, v4, 16, 1
	v_bfe_u32 v7, v3, 16, 1
	v_bfe_u32 v9, v5, 16, 1
	v_add3_u32 v2, v2, v6, s22
	v_add3_u32 v4, v4, v8, s22
	v_add3_u32 v3, v3, v7, s22
	v_add3_u32 v5, v5, v9, s22
	v_lshrrev_b32_e32 v2, 16, v2
	v_lshrrev_b32_e32 v4, 16, v4
	v_and_or_b32 v2, v3, s20, v2
	v_and_or_b32 v3, v5, s20, v4
	global_store_dwordx2 v[38:39], v[2:3], off offset:3584
	s_branch .LBB0_1058

.LBB0_1148:
	s_or_b64 exec, exec, s[2:3]
	v_readfirstlane_b32 s6, v2
	s_cmpk_gt_u32 s6, 0x15ff
	s_mov_b64 s[2:3], -1
	s_cbranch_scc1 .LBB0_1143
	s_and_b32 s4, s6, 0x1fc0
	s_lshl_b32 s2, s6, 5
	s_and_b32 s5, s2, 0x7e0
	s_lshl_b32 s2, s4, 13
	s_add_u32 s2, s86, s2
	s_addc_u32 s3, s87, 0
	s_lshl_b32 s7, s5, 2
	s_add_u32 s2, s2, s7
	s_addc_u32 s3, s3, 0
	v_lshl_add_u64 v[2:3], s[2:3], 0, v[68:69]
	v_lshl_add_u64 v[10:11], v[2:3], 0, v[66:67]
	v_lshl_add_u64 v[2:3], s[2:3], 0, v[70:71]
	v_lshl_add_u64 v[12:13], v[2:3], 0, v[66:67]
	global_load_dwordx4 v[2:5], v[10:11], off nt
	global_load_dwordx4 v[6:9], v[12:13], off nt
	v_lshl_add_u64 v[10:11], s[2:3], 0, v[72:73]
	v_lshl_add_u64 v[18:19], v[10:11], 0, v[66:67]
	v_lshl_add_u64 v[10:11], s[2:3], 0, v[74:75]
	v_lshl_add_u64 v[20:21], v[10:11], 0, v[66:67]
	global_load_dwordx4 v[10:13], v[18:19], off nt
	global_load_dwordx4 v[14:17], v[20:21], off nt
	v_lshl_add_u64 v[18:19], s[2:3], 0, v[76:77]
	v_lshl_add_u64 v[18:19], v[18:19], 0, v[66:67]
	v_lshl_add_u64 v[20:21], s[2:3], 0, v[78:79]
	v_lshl_add_u64 v[20:21], v[20:21], 0, v[66:67]
	s_waitcnt lgkmcnt(0)
	global_load_dwordx4 v[26:29], v[18:19], off nt
	global_load_dwordx4 v[30:33], v[20:21], off nt
	v_lshl_add_u64 v[18:19], s[2:3], 0, v[80:81]
	v_lshl_add_u64 v[18:19], v[18:19], 0, v[66:67]
	global_load_dwordx4 v[42:45], v[18:19], off nt
	v_lshl_add_u64 v[18:19], s[2:3], 0, v[82:83]
	v_lshl_add_u64 v[18:19], v[18:19], 0, v[66:67]
	global_load_dwordx4 v[46:49], v[18:19], off nt
	s_mulk_i32 s5, 0x2c00
	s_add_u32 s2, s8, s5
	s_addc_u32 s3, s9, 0
	s_lshl_b32 s4, s4, 1
	s_add_u32 s4, s2, s4
	s_addc_u32 s5, s3, 0
	s_add_i32 s2, s6, 1
	s_and_b32 s7, s2, 0x3fc0
	s_lshl_b32 s2, s2, 5
	s_and_b32 s2, s2, 0x7e0
	s_lshl_b32 s3, s7, 13
	s_add_u32 s3, s86, s3
	s_mul_i32 s12, s2, 0x2c00
	s_addc_u32 s13, s87, 0
	s_lshl_b32 s2, s2, 2
	s_add_u32 s2, s3, s2
	s_addc_u32 s3, s13, 0
	v_lshl_add_u64 v[18:19], s[2:3], 0, v[68:69]
	v_lshl_add_u64 v[20:21], s[2:3], 0, v[70:71]
	v_lshl_add_u64 v[22:23], s[2:3], 0, v[72:73]
	v_lshl_add_u64 v[24:25], s[2:3], 0, v[74:75]
	v_lshl_add_u64 v[34:35], s[2:3], 0, v[76:77]
	v_lshl_add_u64 v[36:37], s[2:3], 0, v[78:79]
	v_lshl_add_u64 v[38:39], s[2:3], 0, v[80:81]
	v_lshl_add_u64 v[40:41], s[2:3], 0, v[82:83]
	v_lshl_add_u64 v[110:111], v[18:19], 0, v[66:67]
	v_lshl_add_u64 v[112:113], v[20:21], 0, v[66:67]
	v_lshl_add_u64 v[114:115], v[22:23], 0, v[66:67]
	v_lshl_add_u64 v[116:117], v[24:25], 0, v[66:67]
	v_lshl_add_u64 v[118:119], v[34:35], 0, v[66:67]
	v_lshl_add_u64 v[120:121], v[36:37], 0, v[66:67]
	v_lshl_add_u64 v[122:123], v[38:39], 0, v[66:67]
	v_lshl_add_u64 v[124:125], v[40:41], 0, v[66:67]
	global_load_dwordx4 v[62:65], v[110:111], off nt
	global_load_dwordx4 v[58:61], v[112:113], off nt
	global_load_dwordx4 v[54:57], v[114:115], off nt
	global_load_dwordx4 v[50:53], v[116:117], off nt
	global_load_dwordx4 v[38:41], v[118:119], off nt
	global_load_dwordx4 v[34:37], v[120:121], off nt
	global_load_dwordx4 v[22:25], v[122:123], off nt
	global_load_dwordx4 v[18:21], v[124:125], off nt
	v_mov_b32_e32 v93, v67
	s_add_u32 s12, s8, s12
	s_addc_u32 s3, s9, 0
	s_lshl_b32 s2, s7, 1
	s_add_u32 s2, s12, s2
	s_addc_u32 s3, s3, 0
	s_waitcnt vmcnt(0)
	ds_write2_b32 v94, v2, v3 offset1:1
	ds_write2_b32 v94, v4, v5 offset0:2 offset1:3
	ds_write2_b32 v95, v6, v7 offset1:1
	ds_write2_b32 v96, v8, v9 offset1:1
	ds_write2_b32 v97, v10, v11 offset1:1
	ds_write2_b32 v98, v12, v13 offset1:1
	ds_write2_b32 v99, v14, v15 offset1:1
	ds_write2_b32 v100, v16, v17 offset1:1
	ds_write2_b32 v101, v26, v27 offset1:1
	ds_write2_b32 v102, v28, v29 offset1:1
	ds_write2_b32 v103, v30, v31 offset1:1
	ds_write2_b32 v104, v32, v33 offset1:1
	ds_write2_b32 v105, v42, v43 offset1:1
	ds_write2_b32 v106, v44, v45 offset1:1
	ds_write2_b32 v107, v46, v47 offset1:1
	ds_write2_b32 v108, v48, v49 offset1:1
	s_waitcnt lgkmcnt(0)
	ds_read2_b32 v[6:7], v1 offset1:8
	ds_read2_b32 v[10:11], v1 offset0:33 offset1:41
	ds_read2_b32 v[12:13], v1 offset0:66 offset1:74
	ds_read2_b32 v[14:15], v1 offset0:99 offset1:107
	ds_read2_b32 v[16:17], v1 offset0:132 offset1:140
	s_waitcnt lgkmcnt(4)
	v_bfe_u32 v2, v6, 16, 1
	v_add3_u32 v2, v6, v2, s10
	s_waitcnt lgkmcnt(3)
	v_bfe_u32 v3, v10, 16, 1
	v_lshrrev_b32_e32 v2, 16, v2
	v_add3_u32 v3, v10, v3, s10
	ds_read2_b32 v[26:27], v1 offset0:165 offset1:173
	v_and_or_b32 v2, v3, s11, v2
	s_waitcnt lgkmcnt(3)
	v_bfe_u32 v3, v12, 16, 1
	v_add3_u32 v3, v12, v3, s10
	s_waitcnt lgkmcnt(2)
	v_bfe_u32 v4, v14, 16, 1
	ds_read2_b32 v[28:29], v1 offset0:198 offset1:206
	v_lshrrev_b32_e32 v3, 16, v3
	v_add3_u32 v4, v14, v4, s10
	ds_read2_b32 v[30:31], v1 offset0:231 offset1:239
	v_and_or_b32 v3, v4, s11, v3
	s_waitcnt lgkmcnt(3)
	v_bfe_u32 v4, v16, 16, 1
	v_add3_u32 v4, v16, v4, s10
	s_waitcnt lgkmcnt(2)
	v_bfe_u32 v5, v26, 16, 1
	v_lshrrev_b32_e32 v4, 16, v4
	v_add3_u32 v5, v26, v5, s10
	v_and_or_b32 v4, v5, s11, v4
	s_waitcnt lgkmcnt(1)
	v_bfe_u32 v5, v28, 16, 1
	v_add3_u32 v5, v28, v5, s10
	s_waitcnt lgkmcnt(0)
	v_bfe_u32 v6, v30, 16, 1
	v_lshl_add_u64 v[8:9], s[4:5], 0, v[92:93]
	v_lshrrev_b32_e32 v5, 16, v5
	v_add3_u32 v6, v30, v6, s10
	v_and_or_b32 v5, v6, s11, v5
	v_lshl_add_u64 v[32:33], v[8:9], 0, v[84:85]
	global_store_dwordx4 v[32:33], v[2:5], off
	v_bfe_u32 v6, v31, 16, 1
	v_add3_u32 v10, v31, v6, s10
	v_bfe_u32 v2, v7, 16, 1
	v_add3_u32 v2, v7, v2, s10
	v_bfe_u32 v3, v11, 16, 1
	v_lshrrev_b32_e32 v2, 16, v2
	v_add3_u32 v3, v11, v3, s10
	v_and_or_b32 v2, v3, s11, v2
	v_bfe_u32 v3, v13, 16, 1
	v_add3_u32 v3, v13, v3, s10
	v_bfe_u32 v4, v15, 16, 1
	v_lshrrev_b32_e32 v3, 16, v3
	v_add3_u32 v4, v15, v4, s10
	v_and_or_b32 v3, v4, s11, v3
	v_bfe_u32 v4, v17, 16, 1
	v_add3_u32 v4, v17, v4, s10
	v_bfe_u32 v5, v27, 16, 1
	v_lshrrev_b32_e32 v4, 16, v4
	v_add3_u32 v5, v27, v5, s10
	v_and_or_b32 v4, v5, s11, v4
	v_bfe_u32 v5, v29, 16, 1
	v_add3_u32 v5, v29, v5, s10
	v_lshrrev_b32_e32 v5, 16, v5
	ds_read2_b32 v[6:7], v1 offset0:16 offset1:24
	v_and_or_b32 v5, v10, s11, v5
	v_lshl_add_u64 v[10:11], v[8:9], 0, v[86:87]
	global_store_dwordx4 v[10:11], v[2:5], off
	ds_read2_b32 v[10:11], v1 offset0:49 offset1:57
	ds_read2_b32 v[12:13], v1 offset0:82 offset1:90
	ds_read2_b32 v[14:15], v1 offset0:115 offset1:123
	s_waitcnt lgkmcnt(3)
	v_bfe_u32 v2, v6, 16, 1
	v_add3_u32 v2, v6, v2, s10
	s_waitcnt lgkmcnt(2)
	v_bfe_u32 v3, v10, 16, 1
	ds_read2_b32 v[16:17], v1 offset0:148 offset1:156
	v_lshrrev_b32_e32 v2, 16, v2
	v_add3_u32 v3, v10, v3, s10
	ds_read2_b32 v[26:27], v1 offset0:181 offset1:189
	v_and_or_b32 v2, v3, s11, v2
	s_waitcnt lgkmcnt(3)
	v_bfe_u32 v3, v12, 16, 1
	v_add3_u32 v3, v12, v3, s10
	s_waitcnt lgkmcnt(2)
	v_bfe_u32 v4, v14, 16, 1
	ds_read2_b32 v[28:29], v1 offset0:214 offset1:222
	v_lshrrev_b32_e32 v3, 16, v3
	v_add3_u32 v4, v14, v4, s10
	ds_read2_b32 v[30:31], v1 offset0:247 offset1:255
	v_and_or_b32 v3, v4, s11, v3
	s_waitcnt lgkmcnt(3)
	v_bfe_u32 v4, v16, 16, 1
	v_add3_u32 v4, v16, v4, s10
	s_waitcnt lgkmcnt(2)
	v_bfe_u32 v5, v26, 16, 1
	v_lshrrev_b32_e32 v4, 16, v4
	v_add3_u32 v5, v26, v5, s10
	v_and_or_b32 v4, v5, s11, v4
	s_waitcnt lgkmcnt(1)
	v_bfe_u32 v5, v28, 16, 1
	v_add3_u32 v5, v28, v5, s10
	s_waitcnt lgkmcnt(0)
	v_bfe_u32 v6, v30, 16, 1
	v_lshrrev_b32_e32 v5, 16, v5
	v_add3_u32 v6, v30, v6, s10
	v_and_or_b32 v5, v6, s11, v5
	v_lshl_add_u64 v[32:33], v[8:9], 0, v[88:89]
	global_store_dwordx4 v[32:33], v[2:5], off
	s_add_i32 s4, s6, 2
	s_and_b32 s7, s4, 0x3fc0
	v_bfe_u32 v2, v7, 16, 1
	v_add3_u32 v2, v7, v2, s10
	v_bfe_u32 v3, v11, 16, 1
	v_lshrrev_b32_e32 v2, 16, v2
	v_add3_u32 v3, v11, v3, s10
	v_and_or_b32 v2, v3, s11, v2
	v_bfe_u32 v3, v13, 16, 1
	v_add3_u32 v3, v13, v3, s10
	v_bfe_u32 v4, v15, 16, 1
	v_lshrrev_b32_e32 v3, 16, v3
	v_add3_u32 v4, v15, v4, s10
	v_and_or_b32 v3, v4, s11, v3
	v_bfe_u32 v4, v17, 16, 1
	v_add3_u32 v4, v17, v4, s10
	v_bfe_u32 v5, v27, 16, 1
	s_lshl_b32 s5, s7, 13
	v_lshrrev_b32_e32 v4, 16, v4
	v_add3_u32 v5, v27, v5, s10
	s_add_u32 s5, s86, s5
	v_and_or_b32 v4, v5, s11, v4
	v_bfe_u32 v5, v29, 16, 1
	s_addc_u32 s12, s87, 0
	s_lshl_b32 s4, s4, 5
	v_add3_u32 v5, v29, v5, s10
	v_bfe_u32 v6, v31, 16, 1
	s_and_b32 s13, s4, 0x7e0
	v_lshrrev_b32_e32 v5, 16, v5
	v_add3_u32 v6, v31, v6, s10
	s_lshl_b32 s4, s13, 2
	v_and_or_b32 v5, v6, s11, v5
	v_lshl_add_u64 v[6:7], v[8:9], 0, v[90:91]
	s_add_u32 s4, s5, s4
	global_store_dwordx4 v[6:7], v[2:5], off
	s_addc_u32 s5, s12, 0
	s_waitcnt lgkmcnt(0)
	s_mulk_i32 s13, 0x2c00
	v_lshl_add_u64 v[2:3], s[4:5], 0, v[68:69]
	v_lshl_add_u64 v[10:11], v[2:3], 0, v[66:67]
	v_lshl_add_u64 v[2:3], s[4:5], 0, v[70:71]
	v_lshl_add_u64 v[12:13], v[2:3], 0, v[66:67]
	global_load_dwordx4 v[6:9], v[10:11], off nt
	global_load_dwordx4 v[2:5], v[12:13], off nt
	v_lshl_add_u64 v[10:11], s[4:5], 0, v[72:73]
	v_lshl_add_u64 v[26:27], v[10:11], 0, v[66:67]
	v_lshl_add_u64 v[10:11], s[4:5], 0, v[74:75]
	v_lshl_add_u64 v[28:29], v[10:11], 0, v[66:67]
	global_load_dwordx4 v[14:17], v[26:27], off nt
	global_load_dwordx4 v[10:13], v[28:29], off nt
	v_lshl_add_u64 v[26:27], s[4:5], 0, v[76:77]
	v_lshl_add_u64 v[42:43], v[26:27], 0, v[66:67]
	v_lshl_add_u64 v[26:27], s[4:5], 0, v[78:79]
	v_lshl_add_u64 v[44:45], v[26:27], 0, v[66:67]
	global_load_dwordx4 v[30:33], v[42:43], off nt
	global_load_dwordx4 v[26:29], v[44:45], off nt
	v_lshl_add_u64 v[42:43], s[4:5], 0, v[80:81]
	v_lshl_add_u64 v[110:111], v[42:43], 0, v[66:67]
	v_lshl_add_u64 v[42:43], s[4:5], 0, v[82:83]
	v_lshl_add_u64 v[112:113], v[42:43], 0, v[66:67]
	global_load_dwordx4 v[46:49], v[110:111], off nt
	global_load_dwordx4 v[42:45], v[112:113], off nt
	ds_write2_b32 v94, v62, v63 offset1:1
	ds_write2_b32 v94, v64, v65 offset0:2 offset1:3
	ds_write2_b32 v95, v58, v59 offset1:1
	ds_write2_b32 v96, v60, v61 offset1:1
	ds_write2_b32 v97, v54, v55 offset1:1
	ds_write2_b32 v98, v56, v57 offset1:1
	ds_write2_b32 v99, v50, v51 offset1:1
	ds_write2_b32 v100, v52, v53 offset1:1
	ds_write2_b32 v101, v38, v39 offset1:1
	ds_write2_b32 v102, v40, v41 offset1:1
	ds_write2_b32 v103, v34, v35 offset1:1
	ds_write2_b32 v104, v36, v37 offset1:1
	ds_write2_b32 v105, v22, v23 offset1:1
	ds_write2_b32 v106, v24, v25 offset1:1
	ds_write2_b32 v107, v18, v19 offset1:1
	ds_write2_b32 v108, v20, v21 offset1:1
	s_waitcnt lgkmcnt(0)
	ds_read2_b32 v[22:23], v1 offset1:8
	ds_read2_b32 v[34:35], v1 offset0:33 offset1:41
	ds_read2_b32 v[36:37], v1 offset0:66 offset1:74
	ds_read2_b32 v[38:39], v1 offset0:99 offset1:107
	ds_read2_b32 v[40:41], v1 offset0:132 offset1:140
	s_waitcnt lgkmcnt(4)
	v_bfe_u32 v18, v22, 16, 1
	v_add3_u32 v18, v22, v18, s10
	s_waitcnt lgkmcnt(3)
	v_bfe_u32 v19, v34, 16, 1
	v_lshrrev_b32_e32 v18, 16, v18
	v_add3_u32 v19, v34, v19, s10
	ds_read2_b32 v[50:51], v1 offset0:165 offset1:173
	v_and_or_b32 v18, v19, s11, v18
	s_waitcnt lgkmcnt(3)
	v_bfe_u32 v19, v36, 16, 1
	v_add3_u32 v19, v36, v19, s10
	s_waitcnt lgkmcnt(2)
	v_bfe_u32 v20, v38, 16, 1
	ds_read2_b32 v[52:53], v1 offset0:198 offset1:206
	v_lshrrev_b32_e32 v19, 16, v19
	v_add3_u32 v20, v38, v20, s10
	ds_read2_b32 v[54:55], v1 offset0:231 offset1:239
	v_and_or_b32 v19, v20, s11, v19
	s_waitcnt lgkmcnt(3)
	v_bfe_u32 v20, v40, 16, 1
	v_add3_u32 v20, v40, v20, s10
	s_waitcnt lgkmcnt(2)
	v_bfe_u32 v21, v50, 16, 1
	v_lshrrev_b32_e32 v20, 16, v20
	v_add3_u32 v21, v50, v21, s10
	v_and_or_b32 v20, v21, s11, v20
	s_waitcnt lgkmcnt(1)
	v_bfe_u32 v21, v52, 16, 1
	v_add3_u32 v21, v52, v21, s10
	s_waitcnt lgkmcnt(0)
	v_bfe_u32 v22, v54, 16, 1
	v_lshl_add_u64 v[24:25], s[2:3], 0, v[92:93]
	v_lshrrev_b32_e32 v21, 16, v21
	v_add3_u32 v22, v54, v22, s10
	v_and_or_b32 v21, v22, s11, v21
	v_lshl_add_u64 v[56:57], v[24:25], 0, v[84:85]
	global_store_dwordx4 v[56:57], v[18:21], off
	v_bfe_u32 v22, v55, 16, 1
	v_add3_u32 v34, v55, v22, s10
	v_bfe_u32 v18, v23, 16, 1
	v_add3_u32 v18, v23, v18, s10
	v_bfe_u32 v19, v35, 16, 1
	v_lshrrev_b32_e32 v18, 16, v18
	v_add3_u32 v19, v35, v19, s10
	v_and_or_b32 v18, v19, s11, v18
	v_bfe_u32 v19, v37, 16, 1
	v_add3_u32 v19, v37, v19, s10
	v_bfe_u32 v20, v39, 16, 1
	v_lshrrev_b32_e32 v19, 16, v19
	v_add3_u32 v20, v39, v20, s10
	v_and_or_b32 v19, v20, s11, v19
	v_bfe_u32 v20, v41, 16, 1
	v_add3_u32 v20, v41, v20, s10
	v_bfe_u32 v21, v51, 16, 1
	v_lshrrev_b32_e32 v20, 16, v20
	v_add3_u32 v21, v51, v21, s10
	v_and_or_b32 v20, v21, s11, v20
	v_bfe_u32 v21, v53, 16, 1
	v_add3_u32 v21, v53, v21, s10
	v_lshrrev_b32_e32 v21, 16, v21
	ds_read2_b32 v[22:23], v1 offset0:16 offset1:24
	v_and_or_b32 v21, v34, s11, v21
	v_lshl_add_u64 v[34:35], v[24:25], 0, v[86:87]
	global_store_dwordx4 v[34:35], v[18:21], off
	ds_read2_b32 v[34:35], v1 offset0:49 offset1:57
	ds_read2_b32 v[36:37], v1 offset0:82 offset1:90
	ds_read2_b32 v[38:39], v1 offset0:115 offset1:123
	s_waitcnt lgkmcnt(3)
	v_bfe_u32 v18, v22, 16, 1
	v_add3_u32 v18, v22, v18, s10
	s_waitcnt lgkmcnt(2)
	v_bfe_u32 v19, v34, 16, 1
	ds_read2_b32 v[40:41], v1 offset0:148 offset1:156
	v_lshrrev_b32_e32 v18, 16, v18
	v_add3_u32 v19, v34, v19, s10
	ds_read2_b32 v[50:51], v1 offset0:181 offset1:189
	v_and_or_b32 v18, v19, s11, v18
	s_waitcnt lgkmcnt(3)
	v_bfe_u32 v19, v36, 16, 1
	v_add3_u32 v19, v36, v19, s10
	s_waitcnt lgkmcnt(2)
	v_bfe_u32 v20, v38, 16, 1
	ds_read2_b32 v[52:53], v1 offset0:214 offset1:222
	v_lshrrev_b32_e32 v19, 16, v19
	v_add3_u32 v20, v38, v20, s10
	ds_read2_b32 v[54:55], v1 offset0:247 offset1:255
	v_and_or_b32 v19, v20, s11, v19
	s_waitcnt lgkmcnt(3)
	v_bfe_u32 v20, v40, 16, 1
	v_add3_u32 v20, v40, v20, s10
	s_waitcnt lgkmcnt(2)
	v_bfe_u32 v21, v50, 16, 1
	v_lshrrev_b32_e32 v20, 16, v20
	v_add3_u32 v21, v50, v21, s10
	v_and_or_b32 v20, v21, s11, v20
	s_waitcnt lgkmcnt(1)
	v_bfe_u32 v21, v52, 16, 1
	v_add3_u32 v21, v52, v21, s10
	s_waitcnt lgkmcnt(0)
	v_bfe_u32 v22, v54, 16, 1
	v_lshrrev_b32_e32 v21, 16, v21
	v_add3_u32 v22, v54, v22, s10
	v_and_or_b32 v21, v22, s11, v21
	v_lshl_add_u64 v[56:57], v[24:25], 0, v[88:89]
	global_store_dwordx4 v[56:57], v[18:21], off
	s_add_u32 s4, s8, s13
	s_addc_u32 s5, s9, 0
	v_bfe_u32 v18, v23, 16, 1
	v_add3_u32 v18, v23, v18, s10
	v_bfe_u32 v19, v35, 16, 1
	v_lshrrev_b32_e32 v18, 16, v18
	v_add3_u32 v19, v35, v19, s10
	v_and_or_b32 v18, v19, s11, v18
	v_bfe_u32 v19, v37, 16, 1
	v_add3_u32 v19, v37, v19, s10
	v_bfe_u32 v20, v39, 16, 1
	s_lshl_b32 s7, s7, 1
	v_lshrrev_b32_e32 v19, 16, v19
	v_add3_u32 v20, v39, v20, s10
	s_add_u32 s4, s4, s7
	v_and_or_b32 v19, v20, s11, v19
	v_bfe_u32 v20, v41, 16, 1
	s_addc_u32 s5, s5, 0
	v_add3_u32 v20, v41, v20, s10
	v_bfe_u32 v21, v51, 16, 1
	s_add_i32 s2, s6, 3
	v_lshrrev_b32_e32 v20, 16, v20
	v_add3_u32 v21, v51, v21, s10
	s_and_b32 s7, s2, 0x3fc0
	s_lshl_b32 s2, s2, 5
	v_and_or_b32 v20, v21, s11, v20
	v_bfe_u32 v21, v53, 16, 1
	s_and_b32 s12, s2, 0x7e0
	s_lshl_b32 s2, s7, 13
	v_add3_u32 v21, v53, v21, s10
	v_bfe_u32 v22, v55, 16, 1
	s_add_u32 s2, s86, s2
	v_lshrrev_b32_e32 v21, 16, v21
	v_add3_u32 v22, v55, v22, s10
	s_addc_u32 s3, s87, 0
	s_lshl_b32 s13, s12, 2
	v_and_or_b32 v21, v22, s11, v21
	v_lshl_add_u64 v[22:23], v[24:25], 0, v[90:91]
	s_add_u32 s2, s2, s13
	global_store_dwordx4 v[22:23], v[18:21], off
	s_addc_u32 s3, s3, 0
	s_waitcnt lgkmcnt(0)
	s_mulk_i32 s12, 0x2c00
	v_lshl_add_u64 v[18:19], s[2:3], 0, v[68:69]
	v_lshl_add_u64 v[34:35], v[18:19], 0, v[66:67]
	v_lshl_add_u64 v[18:19], s[2:3], 0, v[70:71]
	v_lshl_add_u64 v[36:37], v[18:19], 0, v[66:67]
	global_load_dwordx4 v[22:25], v[34:35], off nt
	global_load_dwordx4 v[18:21], v[36:37], off nt
	v_lshl_add_u64 v[34:35], s[2:3], 0, v[72:73]
	v_lshl_add_u64 v[50:51], v[34:35], 0, v[66:67]
	v_lshl_add_u64 v[34:35], s[2:3], 0, v[74:75]
	v_lshl_add_u64 v[52:53], v[34:35], 0, v[66:67]
	global_load_dwordx4 v[38:41], v[50:51], off nt
	global_load_dwordx4 v[34:37], v[52:53], off nt
	v_lshl_add_u64 v[50:51], s[2:3], 0, v[76:77]
	v_lshl_add_u64 v[58:59], v[50:51], 0, v[66:67]
	v_lshl_add_u64 v[50:51], s[2:3], 0, v[78:79]
	v_lshl_add_u64 v[60:61], v[50:51], 0, v[66:67]
	global_load_dwordx4 v[54:57], v[58:59], off nt
	global_load_dwordx4 v[50:53], v[60:61], off nt
	v_lshl_add_u64 v[58:59], s[2:3], 0, v[80:81]
	v_lshl_add_u64 v[110:111], v[58:59], 0, v[66:67]
	v_lshl_add_u64 v[58:59], s[2:3], 0, v[82:83]
	v_lshl_add_u64 v[112:113], v[58:59], 0, v[66:67]
	global_load_dwordx4 v[62:65], v[110:111], off nt
	global_load_dwordx4 v[58:61], v[112:113], off nt
	s_waitcnt vmcnt(19)
	ds_write2_b32 v94, v6, v7 offset1:1
	ds_write2_b32 v94, v8, v9 offset0:2 offset1:3
	s_waitcnt vmcnt(18)
	ds_write2_b32 v95, v2, v3 offset1:1
	ds_write2_b32 v96, v4, v5 offset1:1
	s_waitcnt vmcnt(17)
	ds_write2_b32 v97, v14, v15 offset1:1
	ds_write2_b32 v98, v16, v17 offset1:1
	s_waitcnt vmcnt(16)
	ds_write2_b32 v99, v10, v11 offset1:1
	ds_write2_b32 v100, v12, v13 offset1:1
	s_waitcnt vmcnt(15)
	ds_write2_b32 v101, v30, v31 offset1:1
	ds_write2_b32 v102, v32, v33 offset1:1
	s_waitcnt vmcnt(14)
	ds_write2_b32 v103, v26, v27 offset1:1
	ds_write2_b32 v104, v28, v29 offset1:1
	s_waitcnt vmcnt(13)
	ds_write2_b32 v105, v46, v47 offset1:1
	ds_write2_b32 v106, v48, v49 offset1:1
	s_waitcnt vmcnt(12)
	ds_write2_b32 v107, v42, v43 offset1:1
	ds_write2_b32 v108, v44, v45 offset1:1
	s_waitcnt lgkmcnt(0)
	ds_read2_b32 v[6:7], v1 offset1:8
	ds_read2_b32 v[10:11], v1 offset0:33 offset1:41
	ds_read2_b32 v[12:13], v1 offset0:66 offset1:74
	ds_read2_b32 v[14:15], v1 offset0:99 offset1:107
	ds_read2_b32 v[16:17], v1 offset0:132 offset1:140
	s_waitcnt lgkmcnt(4)
	v_bfe_u32 v2, v6, 16, 1
	v_add3_u32 v2, v6, v2, s10
	s_waitcnt lgkmcnt(3)
	v_bfe_u32 v3, v10, 16, 1
	v_lshrrev_b32_e32 v2, 16, v2
	v_add3_u32 v3, v10, v3, s10
	ds_read2_b32 v[26:27], v1 offset0:165 offset1:173
	v_and_or_b32 v2, v3, s11, v2
	s_waitcnt lgkmcnt(3)
	v_bfe_u32 v3, v12, 16, 1
	v_add3_u32 v3, v12, v3, s10
	s_waitcnt lgkmcnt(2)
	v_bfe_u32 v4, v14, 16, 1
	ds_read2_b32 v[28:29], v1 offset0:198 offset1:206
	v_lshrrev_b32_e32 v3, 16, v3
	v_add3_u32 v4, v14, v4, s10
	ds_read2_b32 v[30:31], v1 offset0:231 offset1:239
	v_and_or_b32 v3, v4, s11, v3
	s_waitcnt lgkmcnt(3)
	v_bfe_u32 v4, v16, 16, 1
	v_add3_u32 v4, v16, v4, s10
	s_waitcnt lgkmcnt(2)
	v_bfe_u32 v5, v26, 16, 1
	v_lshrrev_b32_e32 v4, 16, v4
	v_add3_u32 v5, v26, v5, s10
	v_and_or_b32 v4, v5, s11, v4
	s_waitcnt lgkmcnt(1)
	v_bfe_u32 v5, v28, 16, 1
	v_add3_u32 v5, v28, v5, s10
	s_waitcnt lgkmcnt(0)
	v_bfe_u32 v6, v30, 16, 1
	v_lshl_add_u64 v[8:9], s[4:5], 0, v[92:93]
	v_lshrrev_b32_e32 v5, 16, v5
	v_add3_u32 v6, v30, v6, s10
	v_and_or_b32 v5, v6, s11, v5
	v_lshl_add_u64 v[32:33], v[8:9], 0, v[84:85]
	global_store_dwordx4 v[32:33], v[2:5], off
	v_bfe_u32 v6, v31, 16, 1
	v_add3_u32 v10, v31, v6, s10
	v_bfe_u32 v2, v7, 16, 1
	v_add3_u32 v2, v7, v2, s10
	v_bfe_u32 v3, v11, 16, 1
	v_lshrrev_b32_e32 v2, 16, v2
	v_add3_u32 v3, v11, v3, s10
	v_and_or_b32 v2, v3, s11, v2
	v_bfe_u32 v3, v13, 16, 1
	v_add3_u32 v3, v13, v3, s10
	v_bfe_u32 v4, v15, 16, 1
	v_lshrrev_b32_e32 v3, 16, v3
	v_add3_u32 v4, v15, v4, s10
	v_and_or_b32 v3, v4, s11, v3
	v_bfe_u32 v4, v17, 16, 1
	v_add3_u32 v4, v17, v4, s10
	v_bfe_u32 v5, v27, 16, 1
	v_lshrrev_b32_e32 v4, 16, v4
	v_add3_u32 v5, v27, v5, s10
	v_and_or_b32 v4, v5, s11, v4
	v_bfe_u32 v5, v29, 16, 1
	v_add3_u32 v5, v29, v5, s10
	v_lshrrev_b32_e32 v5, 16, v5
	ds_read2_b32 v[6:7], v1 offset0:16 offset1:24
	v_and_or_b32 v5, v10, s11, v5
	v_lshl_add_u64 v[10:11], v[8:9], 0, v[86:87]
	global_store_dwordx4 v[10:11], v[2:5], off
	ds_read2_b32 v[10:11], v1 offset0:49 offset1:57
	ds_read2_b32 v[12:13], v1 offset0:82 offset1:90
	ds_read2_b32 v[14:15], v1 offset0:115 offset1:123
	s_waitcnt lgkmcnt(3)
	v_bfe_u32 v2, v6, 16, 1
	v_add3_u32 v2, v6, v2, s10
	s_waitcnt lgkmcnt(2)
	v_bfe_u32 v3, v10, 16, 1
	ds_read2_b32 v[16:17], v1 offset0:148 offset1:156
	v_lshrrev_b32_e32 v2, 16, v2
	v_add3_u32 v3, v10, v3, s10
	ds_read2_b32 v[26:27], v1 offset0:181 offset1:189
	v_and_or_b32 v2, v3, s11, v2
	s_waitcnt lgkmcnt(3)
	v_bfe_u32 v3, v12, 16, 1
	v_add3_u32 v3, v12, v3, s10
	s_waitcnt lgkmcnt(2)
	v_bfe_u32 v4, v14, 16, 1
	ds_read2_b32 v[28:29], v1 offset0:214 offset1:222
	v_lshrrev_b32_e32 v3, 16, v3
	v_add3_u32 v4, v14, v4, s10
	ds_read2_b32 v[30:31], v1 offset0:247 offset1:255
	v_and_or_b32 v3, v4, s11, v3
	s_waitcnt lgkmcnt(3)
	v_bfe_u32 v4, v16, 16, 1
	v_add3_u32 v4, v16, v4, s10
	s_waitcnt lgkmcnt(2)
	v_bfe_u32 v5, v26, 16, 1
	v_lshrrev_b32_e32 v4, 16, v4
	v_add3_u32 v5, v26, v5, s10
	v_and_or_b32 v4, v5, s11, v4
	s_waitcnt lgkmcnt(1)
	v_bfe_u32 v5, v28, 16, 1
	v_add3_u32 v5, v28, v5, s10
	s_waitcnt lgkmcnt(0)
	v_bfe_u32 v6, v30, 16, 1
	v_lshrrev_b32_e32 v5, 16, v5
	v_add3_u32 v6, v30, v6, s10
	v_and_or_b32 v5, v6, s11, v5
	v_lshl_add_u64 v[32:33], v[8:9], 0, v[88:89]
	global_store_dwordx4 v[32:33], v[2:5], off
	s_add_u32 s12, s8, s12
	s_addc_u32 s13, s9, 0
	v_bfe_u32 v2, v7, 16, 1
	v_add3_u32 v2, v7, v2, s10
	v_bfe_u32 v3, v11, 16, 1
	v_lshrrev_b32_e32 v2, 16, v2
	v_add3_u32 v3, v11, v3, s10
	s_lshl_b32 s7, s7, 1
	v_and_or_b32 v2, v3, s11, v2
	v_bfe_u32 v3, v13, 16, 1
	s_add_u32 s2, s12, s7
	v_add3_u32 v3, v13, v3, s10
	v_bfe_u32 v4, v15, 16, 1
	s_addc_u32 s3, s13, 0
	v_lshrrev_b32_e32 v3, 16, v3
	v_add3_u32 v4, v15, v4, s10
	s_add_i32 s4, s6, 4
	v_and_or_b32 v3, v4, s11, v3
	v_bfe_u32 v4, v17, 16, 1
	s_and_b32 s7, s4, 0x3fc0
	v_add3_u32 v4, v17, v4, s10
	v_bfe_u32 v5, v27, 16, 1
	s_lshl_b32 s5, s7, 13
	v_lshrrev_b32_e32 v4, 16, v4
	v_add3_u32 v5, v27, v5, s10
	s_add_u32 s5, s86, s5
	v_and_or_b32 v4, v5, s11, v4
	v_bfe_u32 v5, v29, 16, 1
	s_addc_u32 s12, s87, 0
	s_lshl_b32 s4, s4, 5
	v_add3_u32 v5, v29, v5, s10
	v_bfe_u32 v6, v31, 16, 1
	s_and_b32 s13, s4, 0x7e0
	v_lshrrev_b32_e32 v5, 16, v5
	v_add3_u32 v6, v31, v6, s10
	s_lshl_b32 s4, s13, 2
	v_and_or_b32 v5, v6, s11, v5
	v_lshl_add_u64 v[6:7], v[8:9], 0, v[90:91]
	s_add_u32 s4, s5, s4
	global_store_dwordx4 v[6:7], v[2:5], off
	s_addc_u32 s5, s12, 0
	s_waitcnt lgkmcnt(0)
	s_mulk_i32 s13, 0x2c00
	v_lshl_add_u64 v[2:3], s[4:5], 0, v[68:69]
	v_lshl_add_u64 v[10:11], v[2:3], 0, v[66:67]
	v_lshl_add_u64 v[2:3], s[4:5], 0, v[70:71]
	v_lshl_add_u64 v[12:13], v[2:3], 0, v[66:67]
	global_load_dwordx4 v[6:9], v[10:11], off nt
	global_load_dwordx4 v[2:5], v[12:13], off nt
	v_lshl_add_u64 v[10:11], s[4:5], 0, v[72:73]
	v_lshl_add_u64 v[26:27], v[10:11], 0, v[66:67]
	v_lshl_add_u64 v[10:11], s[4:5], 0, v[74:75]
	v_lshl_add_u64 v[28:29], v[10:11], 0, v[66:67]
	global_load_dwordx4 v[14:17], v[26:27], off nt
	global_load_dwordx4 v[10:13], v[28:29], off nt
	v_lshl_add_u64 v[26:27], s[4:5], 0, v[76:77]
	v_lshl_add_u64 v[42:43], v[26:27], 0, v[66:67]
	v_lshl_add_u64 v[26:27], s[4:5], 0, v[78:79]
	v_lshl_add_u64 v[44:45], v[26:27], 0, v[66:67]
	global_load_dwordx4 v[30:33], v[42:43], off nt
	global_load_dwordx4 v[26:29], v[44:45], off nt
	v_lshl_add_u64 v[42:43], s[4:5], 0, v[80:81]
	v_lshl_add_u64 v[110:111], v[42:43], 0, v[66:67]
	v_lshl_add_u64 v[42:43], s[4:5], 0, v[82:83]
	v_lshl_add_u64 v[112:113], v[42:43], 0, v[66:67]
	global_load_dwordx4 v[46:49], v[110:111], off nt
	global_load_dwordx4 v[42:45], v[112:113], off nt
	s_waitcnt vmcnt(19)
	ds_write2_b32 v94, v22, v23 offset1:1
	ds_write2_b32 v94, v24, v25 offset0:2 offset1:3
	s_waitcnt vmcnt(18)
	ds_write2_b32 v95, v18, v19 offset1:1
	ds_write2_b32 v96, v20, v21 offset1:1
	s_waitcnt vmcnt(17)
	ds_write2_b32 v97, v38, v39 offset1:1
	ds_write2_b32 v98, v40, v41 offset1:1
	s_waitcnt vmcnt(16)
	ds_write2_b32 v99, v34, v35 offset1:1
	ds_write2_b32 v100, v36, v37 offset1:1
	s_waitcnt vmcnt(15)
	ds_write2_b32 v101, v54, v55 offset1:1
	ds_write2_b32 v102, v56, v57 offset1:1
	s_waitcnt vmcnt(14)
	ds_write2_b32 v103, v50, v51 offset1:1
	ds_write2_b32 v104, v52, v53 offset1:1
	s_waitcnt vmcnt(13)
	ds_write2_b32 v105, v62, v63 offset1:1
	ds_write2_b32 v106, v64, v65 offset1:1
	s_waitcnt vmcnt(12)
	ds_write2_b32 v107, v58, v59 offset1:1
	ds_write2_b32 v108, v60, v61 offset1:1
	s_waitcnt lgkmcnt(0)
	ds_read2_b32 v[22:23], v1 offset1:8
	ds_read2_b32 v[34:35], v1 offset0:33 offset1:41
	ds_read2_b32 v[36:37], v1 offset0:66 offset1:74
	ds_read2_b32 v[38:39], v1 offset0:99 offset1:107
	ds_read2_b32 v[40:41], v1 offset0:132 offset1:140
	s_waitcnt lgkmcnt(4)
	v_bfe_u32 v18, v22, 16, 1
	v_add3_u32 v18, v22, v18, s10
	s_waitcnt lgkmcnt(3)
	v_bfe_u32 v19, v34, 16, 1
	v_lshrrev_b32_e32 v18, 16, v18
	v_add3_u32 v19, v34, v19, s10
	ds_read2_b32 v[50:51], v1 offset0:165 offset1:173
	v_and_or_b32 v18, v19, s11, v18
	s_waitcnt lgkmcnt(3)
	v_bfe_u32 v19, v36, 16, 1
	v_add3_u32 v19, v36, v19, s10
	s_waitcnt lgkmcnt(2)
	v_bfe_u32 v20, v38, 16, 1
	ds_read2_b32 v[52:53], v1 offset0:198 offset1:206
	v_lshrrev_b32_e32 v19, 16, v19
	v_add3_u32 v20, v38, v20, s10
	ds_read2_b32 v[54:55], v1 offset0:231 offset1:239
	v_and_or_b32 v19, v20, s11, v19
	s_waitcnt lgkmcnt(3)
	v_bfe_u32 v20, v40, 16, 1
	v_add3_u32 v20, v40, v20, s10
	s_waitcnt lgkmcnt(2)
	v_bfe_u32 v21, v50, 16, 1
	v_lshrrev_b32_e32 v20, 16, v20
	v_add3_u32 v21, v50, v21, s10
	v_and_or_b32 v20, v21, s11, v20
	s_waitcnt lgkmcnt(1)
	v_bfe_u32 v21, v52, 16, 1
	v_add3_u32 v21, v52, v21, s10
	s_waitcnt lgkmcnt(0)
	v_bfe_u32 v22, v54, 16, 1
	v_lshl_add_u64 v[24:25], s[2:3], 0, v[92:93]
	v_lshrrev_b32_e32 v21, 16, v21
	v_add3_u32 v22, v54, v22, s10
	v_and_or_b32 v21, v22, s11, v21
	v_lshl_add_u64 v[56:57], v[24:25], 0, v[84:85]
	global_store_dwordx4 v[56:57], v[18:21], off
	v_bfe_u32 v22, v55, 16, 1
	v_add3_u32 v34, v55, v22, s10
	v_bfe_u32 v18, v23, 16, 1
	v_add3_u32 v18, v23, v18, s10
	v_bfe_u32 v19, v35, 16, 1
	v_lshrrev_b32_e32 v18, 16, v18
	v_add3_u32 v19, v35, v19, s10
	v_and_or_b32 v18, v19, s11, v18
	v_bfe_u32 v19, v37, 16, 1
	v_add3_u32 v19, v37, v19, s10
	v_bfe_u32 v20, v39, 16, 1
	v_lshrrev_b32_e32 v19, 16, v19
	v_add3_u32 v20, v39, v20, s10
	v_and_or_b32 v19, v20, s11, v19
	v_bfe_u32 v20, v41, 16, 1
	v_add3_u32 v20, v41, v20, s10
	v_bfe_u32 v21, v51, 16, 1
	v_lshrrev_b32_e32 v20, 16, v20
	v_add3_u32 v21, v51, v21, s10
	v_and_or_b32 v20, v21, s11, v20
	v_bfe_u32 v21, v53, 16, 1
	v_add3_u32 v21, v53, v21, s10
	v_lshrrev_b32_e32 v21, 16, v21
	ds_read2_b32 v[22:23], v1 offset0:16 offset1:24
	v_and_or_b32 v21, v34, s11, v21
	v_lshl_add_u64 v[34:35], v[24:25], 0, v[86:87]
	global_store_dwordx4 v[34:35], v[18:21], off
	ds_read2_b32 v[34:35], v1 offset0:49 offset1:57
	ds_read2_b32 v[36:37], v1 offset0:82 offset1:90
	ds_read2_b32 v[38:39], v1 offset0:115 offset1:123
	s_waitcnt lgkmcnt(3)
	v_bfe_u32 v18, v22, 16, 1
	v_add3_u32 v18, v22, v18, s10
	s_waitcnt lgkmcnt(2)
	v_bfe_u32 v19, v34, 16, 1
	ds_read2_b32 v[40:41], v1 offset0:148 offset1:156
	v_lshrrev_b32_e32 v18, 16, v18
	v_add3_u32 v19, v34, v19, s10
	ds_read2_b32 v[50:51], v1 offset0:181 offset1:189
	v_and_or_b32 v18, v19, s11, v18
	s_waitcnt lgkmcnt(3)
	v_bfe_u32 v19, v36, 16, 1
	v_add3_u32 v19, v36, v19, s10
	s_waitcnt lgkmcnt(2)
	v_bfe_u32 v20, v38, 16, 1
	ds_read2_b32 v[52:53], v1 offset0:214 offset1:222
	v_lshrrev_b32_e32 v19, 16, v19
	v_add3_u32 v20, v38, v20, s10
	ds_read2_b32 v[54:55], v1 offset0:247 offset1:255
	v_and_or_b32 v19, v20, s11, v19
	s_waitcnt lgkmcnt(3)
	v_bfe_u32 v20, v40, 16, 1
	v_add3_u32 v20, v40, v20, s10
	s_waitcnt lgkmcnt(2)
	v_bfe_u32 v21, v50, 16, 1
	v_lshrrev_b32_e32 v20, 16, v20
	v_add3_u32 v21, v50, v21, s10
	v_and_or_b32 v20, v21, s11, v20
	s_waitcnt lgkmcnt(1)
	v_bfe_u32 v21, v52, 16, 1
	v_add3_u32 v21, v52, v21, s10
	s_waitcnt lgkmcnt(0)
	v_bfe_u32 v22, v54, 16, 1
	v_lshrrev_b32_e32 v21, 16, v21
	v_add3_u32 v22, v54, v22, s10
	v_and_or_b32 v21, v22, s11, v21
	v_lshl_add_u64 v[56:57], v[24:25], 0, v[88:89]
	global_store_dwordx4 v[56:57], v[18:21], off
	s_add_u32 s4, s8, s13
	s_addc_u32 s5, s9, 0
	v_bfe_u32 v18, v23, 16, 1
	v_add3_u32 v18, v23, v18, s10
	v_bfe_u32 v19, v35, 16, 1
	v_lshrrev_b32_e32 v18, 16, v18
	v_add3_u32 v19, v35, v19, s10
	v_and_or_b32 v18, v19, s11, v18
	v_bfe_u32 v19, v37, 16, 1
	v_add3_u32 v19, v37, v19, s10
	v_bfe_u32 v20, v39, 16, 1
	s_lshl_b32 s7, s7, 1
	v_lshrrev_b32_e32 v19, 16, v19
	v_add3_u32 v20, v39, v20, s10
	s_add_u32 s4, s4, s7
	v_and_or_b32 v19, v20, s11, v19
	v_bfe_u32 v20, v41, 16, 1
	s_addc_u32 s5, s5, 0
	v_add3_u32 v20, v41, v20, s10
	v_bfe_u32 v21, v51, 16, 1
	s_add_i32 s2, s6, 5
	v_lshrrev_b32_e32 v20, 16, v20
	v_add3_u32 v21, v51, v21, s10
	s_and_b32 s7, s2, 0x3fc0
	s_lshl_b32 s2, s2, 5
	v_and_or_b32 v20, v21, s11, v20
	v_bfe_u32 v21, v53, 16, 1
	s_and_b32 s12, s2, 0x7e0
	s_lshl_b32 s2, s7, 13
	v_add3_u32 v21, v53, v21, s10
	v_bfe_u32 v22, v55, 16, 1
	s_add_u32 s2, s86, s2
	v_lshrrev_b32_e32 v21, 16, v21
	v_add3_u32 v22, v55, v22, s10
	s_addc_u32 s3, s87, 0
	s_lshl_b32 s13, s12, 2
	v_and_or_b32 v21, v22, s11, v21
	v_lshl_add_u64 v[22:23], v[24:25], 0, v[90:91]
	s_add_u32 s2, s2, s13
	global_store_dwordx4 v[22:23], v[18:21], off
	s_addc_u32 s3, s3, 0
	s_waitcnt lgkmcnt(0)
	s_mulk_i32 s12, 0x2c00
	v_lshl_add_u64 v[18:19], s[2:3], 0, v[68:69]
	v_lshl_add_u64 v[34:35], v[18:19], 0, v[66:67]
	v_lshl_add_u64 v[18:19], s[2:3], 0, v[70:71]
	v_lshl_add_u64 v[36:37], v[18:19], 0, v[66:67]
	global_load_dwordx4 v[22:25], v[34:35], off nt
	global_load_dwordx4 v[18:21], v[36:37], off nt
	v_lshl_add_u64 v[34:35], s[2:3], 0, v[72:73]
	v_lshl_add_u64 v[50:51], v[34:35], 0, v[66:67]
	v_lshl_add_u64 v[34:35], s[2:3], 0, v[74:75]
	v_lshl_add_u64 v[52:53], v[34:35], 0, v[66:67]
	global_load_dwordx4 v[38:41], v[50:51], off nt
	global_load_dwordx4 v[34:37], v[52:53], off nt
	v_lshl_add_u64 v[50:51], s[2:3], 0, v[76:77]
	v_lshl_add_u64 v[58:59], v[50:51], 0, v[66:67]
	v_lshl_add_u64 v[50:51], s[2:3], 0, v[78:79]
	v_lshl_add_u64 v[60:61], v[50:51], 0, v[66:67]
	global_load_dwordx4 v[54:57], v[58:59], off nt
	global_load_dwordx4 v[50:53], v[60:61], off nt
	v_lshl_add_u64 v[58:59], s[2:3], 0, v[80:81]
	v_lshl_add_u64 v[110:111], v[58:59], 0, v[66:67]
	v_lshl_add_u64 v[58:59], s[2:3], 0, v[82:83]
	v_lshl_add_u64 v[112:113], v[58:59], 0, v[66:67]
	global_load_dwordx4 v[62:65], v[110:111], off nt
	global_load_dwordx4 v[58:61], v[112:113], off nt
	s_waitcnt vmcnt(19)
	ds_write2_b32 v94, v6, v7 offset1:1
	ds_write2_b32 v94, v8, v9 offset0:2 offset1:3
	s_waitcnt vmcnt(18)
	ds_write2_b32 v95, v2, v3 offset1:1
	ds_write2_b32 v96, v4, v5 offset1:1
	s_waitcnt vmcnt(17)
	ds_write2_b32 v97, v14, v15 offset1:1
	ds_write2_b32 v98, v16, v17 offset1:1
	s_waitcnt vmcnt(16)
	ds_write2_b32 v99, v10, v11 offset1:1
	ds_write2_b32 v100, v12, v13 offset1:1
	s_waitcnt vmcnt(15)
	ds_write2_b32 v101, v30, v31 offset1:1
	ds_write2_b32 v102, v32, v33 offset1:1
	s_waitcnt vmcnt(14)
	ds_write2_b32 v103, v26, v27 offset1:1
	ds_write2_b32 v104, v28, v29 offset1:1
	s_waitcnt vmcnt(13)
	ds_write2_b32 v105, v46, v47 offset1:1
	ds_write2_b32 v106, v48, v49 offset1:1
	s_waitcnt vmcnt(12)
	ds_write2_b32 v107, v42, v43 offset1:1
	ds_write2_b32 v108, v44, v45 offset1:1
	s_waitcnt lgkmcnt(0)
	ds_read2_b32 v[6:7], v1 offset1:8
	ds_read2_b32 v[10:11], v1 offset0:33 offset1:41
	ds_read2_b32 v[12:13], v1 offset0:66 offset1:74
	ds_read2_b32 v[14:15], v1 offset0:99 offset1:107
	ds_read2_b32 v[16:17], v1 offset0:132 offset1:140
	s_waitcnt lgkmcnt(4)
	v_bfe_u32 v2, v6, 16, 1
	v_add3_u32 v2, v6, v2, s10
	s_waitcnt lgkmcnt(3)
	v_bfe_u32 v3, v10, 16, 1
	v_lshrrev_b32_e32 v2, 16, v2
	v_add3_u32 v3, v10, v3, s10
	ds_read2_b32 v[26:27], v1 offset0:165 offset1:173
	v_and_or_b32 v2, v3, s11, v2
	s_waitcnt lgkmcnt(3)
	v_bfe_u32 v3, v12, 16, 1
	v_add3_u32 v3, v12, v3, s10
	s_waitcnt lgkmcnt(2)
	v_bfe_u32 v4, v14, 16, 1
	ds_read2_b32 v[28:29], v1 offset0:198 offset1:206
	v_lshrrev_b32_e32 v3, 16, v3
	v_add3_u32 v4, v14, v4, s10
	ds_read2_b32 v[30:31], v1 offset0:231 offset1:239
	v_and_or_b32 v3, v4, s11, v3
	s_waitcnt lgkmcnt(3)
	v_bfe_u32 v4, v16, 16, 1
	v_add3_u32 v4, v16, v4, s10
	s_waitcnt lgkmcnt(2)
	v_bfe_u32 v5, v26, 16, 1
	v_lshrrev_b32_e32 v4, 16, v4
	v_add3_u32 v5, v26, v5, s10
	v_and_or_b32 v4, v5, s11, v4
	s_waitcnt lgkmcnt(1)
	v_bfe_u32 v5, v28, 16, 1
	v_add3_u32 v5, v28, v5, s10
	s_waitcnt lgkmcnt(0)
	v_bfe_u32 v6, v30, 16, 1
	v_lshl_add_u64 v[8:9], s[4:5], 0, v[92:93]
	v_lshrrev_b32_e32 v5, 16, v5
	v_add3_u32 v6, v30, v6, s10
	v_and_or_b32 v5, v6, s11, v5
	v_lshl_add_u64 v[32:33], v[8:9], 0, v[84:85]
	global_store_dwordx4 v[32:33], v[2:5], off
	v_bfe_u32 v6, v31, 16, 1
	v_add3_u32 v10, v31, v6, s10
	v_bfe_u32 v2, v7, 16, 1
	v_add3_u32 v2, v7, v2, s10
	v_bfe_u32 v3, v11, 16, 1
	v_lshrrev_b32_e32 v2, 16, v2
	v_add3_u32 v3, v11, v3, s10
	v_and_or_b32 v2, v3, s11, v2
	v_bfe_u32 v3, v13, 16, 1
	v_add3_u32 v3, v13, v3, s10
	v_bfe_u32 v4, v15, 16, 1
	v_lshrrev_b32_e32 v3, 16, v3
	v_add3_u32 v4, v15, v4, s10
	v_and_or_b32 v3, v4, s11, v3
	v_bfe_u32 v4, v17, 16, 1
	v_add3_u32 v4, v17, v4, s10
	v_bfe_u32 v5, v27, 16, 1
	v_lshrrev_b32_e32 v4, 16, v4
	v_add3_u32 v5, v27, v5, s10
	v_and_or_b32 v4, v5, s11, v4
	v_bfe_u32 v5, v29, 16, 1
	v_add3_u32 v5, v29, v5, s10
	v_lshrrev_b32_e32 v5, 16, v5
	ds_read2_b32 v[6:7], v1 offset0:16 offset1:24
	v_and_or_b32 v5, v10, s11, v5
	v_lshl_add_u64 v[10:11], v[8:9], 0, v[86:87]
	global_store_dwordx4 v[10:11], v[2:5], off
	ds_read2_b32 v[10:11], v1 offset0:49 offset1:57
	ds_read2_b32 v[12:13], v1 offset0:82 offset1:90
	ds_read2_b32 v[14:15], v1 offset0:115 offset1:123
	s_waitcnt lgkmcnt(3)
	v_bfe_u32 v2, v6, 16, 1
	v_add3_u32 v2, v6, v2, s10
	s_waitcnt lgkmcnt(2)
	v_bfe_u32 v3, v10, 16, 1
	ds_read2_b32 v[16:17], v1 offset0:148 offset1:156
	v_lshrrev_b32_e32 v2, 16, v2
	v_add3_u32 v3, v10, v3, s10
	ds_read2_b32 v[26:27], v1 offset0:181 offset1:189
	v_and_or_b32 v2, v3, s11, v2
	s_waitcnt lgkmcnt(3)
	v_bfe_u32 v3, v12, 16, 1
	v_add3_u32 v3, v12, v3, s10
	s_waitcnt lgkmcnt(2)
	v_bfe_u32 v4, v14, 16, 1
	ds_read2_b32 v[28:29], v1 offset0:214 offset1:222
	v_lshrrev_b32_e32 v3, 16, v3
	v_add3_u32 v4, v14, v4, s10
	ds_read2_b32 v[30:31], v1 offset0:247 offset1:255
	v_and_or_b32 v3, v4, s11, v3
	s_waitcnt lgkmcnt(3)
	v_bfe_u32 v4, v16, 16, 1
	v_add3_u32 v4, v16, v4, s10
	s_waitcnt lgkmcnt(2)
	v_bfe_u32 v5, v26, 16, 1
	v_lshrrev_b32_e32 v4, 16, v4
	v_add3_u32 v5, v26, v5, s10
	v_and_or_b32 v4, v5, s11, v4
	s_waitcnt lgkmcnt(1)
	v_bfe_u32 v5, v28, 16, 1
	v_add3_u32 v5, v28, v5, s10
	s_waitcnt lgkmcnt(0)
	v_bfe_u32 v6, v30, 16, 1
	v_lshrrev_b32_e32 v5, 16, v5
	v_add3_u32 v6, v30, v6, s10
	v_and_or_b32 v5, v6, s11, v5
	v_lshl_add_u64 v[32:33], v[8:9], 0, v[88:89]
	global_store_dwordx4 v[32:33], v[2:5], off
	s_add_u32 s12, s8, s12
	s_addc_u32 s13, s9, 0
	v_bfe_u32 v2, v7, 16, 1
	v_add3_u32 v2, v7, v2, s10
	v_bfe_u32 v3, v11, 16, 1
	v_lshrrev_b32_e32 v2, 16, v2
	v_add3_u32 v3, v11, v3, s10
	s_lshl_b32 s7, s7, 1
	v_and_or_b32 v2, v3, s11, v2
	v_bfe_u32 v3, v13, 16, 1
	s_add_u32 s2, s12, s7
	v_add3_u32 v3, v13, v3, s10
	v_bfe_u32 v4, v15, 16, 1
	s_addc_u32 s3, s13, 0
	v_lshrrev_b32_e32 v3, 16, v3
	v_add3_u32 v4, v15, v4, s10
	s_add_i32 s4, s6, 6
	v_and_or_b32 v3, v4, s11, v3
	v_bfe_u32 v4, v17, 16, 1
	s_and_b32 s7, s4, 0x3fc0
	v_add3_u32 v4, v17, v4, s10
	v_bfe_u32 v5, v27, 16, 1
	s_lshl_b32 s5, s7, 13
	v_lshrrev_b32_e32 v4, 16, v4
	v_add3_u32 v5, v27, v5, s10
	s_add_u32 s5, s86, s5
	v_and_or_b32 v4, v5, s11, v4
	v_bfe_u32 v5, v29, 16, 1
	s_addc_u32 s12, s87, 0
	s_lshl_b32 s4, s4, 5
	v_add3_u32 v5, v29, v5, s10
	v_bfe_u32 v6, v31, 16, 1
	s_and_b32 s13, s4, 0x7e0
	v_lshrrev_b32_e32 v5, 16, v5
	v_add3_u32 v6, v31, v6, s10
	s_lshl_b32 s4, s13, 2
	v_and_or_b32 v5, v6, s11, v5
	v_lshl_add_u64 v[6:7], v[8:9], 0, v[90:91]
	s_add_u32 s4, s5, s4
	global_store_dwordx4 v[6:7], v[2:5], off
	s_addc_u32 s5, s12, 0
	s_waitcnt lgkmcnt(0)
	s_mulk_i32 s13, 0x2c00
	v_lshl_add_u64 v[2:3], s[4:5], 0, v[68:69]
	v_lshl_add_u64 v[10:11], v[2:3], 0, v[66:67]
	v_lshl_add_u64 v[2:3], s[4:5], 0, v[70:71]
	v_lshl_add_u64 v[12:13], v[2:3], 0, v[66:67]
	global_load_dwordx4 v[6:9], v[10:11], off nt
	global_load_dwordx4 v[2:5], v[12:13], off nt
	v_lshl_add_u64 v[10:11], s[4:5], 0, v[72:73]
	v_lshl_add_u64 v[26:27], v[10:11], 0, v[66:67]
	v_lshl_add_u64 v[10:11], s[4:5], 0, v[74:75]
	v_lshl_add_u64 v[28:29], v[10:11], 0, v[66:67]
	global_load_dwordx4 v[14:17], v[26:27], off nt
	global_load_dwordx4 v[10:13], v[28:29], off nt
	v_lshl_add_u64 v[26:27], s[4:5], 0, v[76:77]
	v_lshl_add_u64 v[42:43], v[26:27], 0, v[66:67]
	v_lshl_add_u64 v[26:27], s[4:5], 0, v[78:79]
	v_lshl_add_u64 v[44:45], v[26:27], 0, v[66:67]
	global_load_dwordx4 v[30:33], v[42:43], off nt
	global_load_dwordx4 v[26:29], v[44:45], off nt
	v_lshl_add_u64 v[42:43], s[4:5], 0, v[80:81]
	v_lshl_add_u64 v[110:111], v[42:43], 0, v[66:67]
	v_lshl_add_u64 v[42:43], s[4:5], 0, v[82:83]
	v_lshl_add_u64 v[112:113], v[42:43], 0, v[66:67]
	global_load_dwordx4 v[46:49], v[110:111], off nt
	global_load_dwordx4 v[42:45], v[112:113], off nt
	s_waitcnt vmcnt(19)
	ds_write2_b32 v94, v22, v23 offset1:1
	ds_write2_b32 v94, v24, v25 offset0:2 offset1:3
	s_waitcnt vmcnt(18)
	ds_write2_b32 v95, v18, v19 offset1:1
	ds_write2_b32 v96, v20, v21 offset1:1
	s_waitcnt vmcnt(17)
	ds_write2_b32 v97, v38, v39 offset1:1
	ds_write2_b32 v98, v40, v41 offset1:1
	s_waitcnt vmcnt(16)
	ds_write2_b32 v99, v34, v35 offset1:1
	ds_write2_b32 v100, v36, v37 offset1:1
	s_waitcnt vmcnt(15)
	ds_write2_b32 v101, v54, v55 offset1:1
	ds_write2_b32 v102, v56, v57 offset1:1
	s_waitcnt vmcnt(14)
	ds_write2_b32 v103, v50, v51 offset1:1
	ds_write2_b32 v104, v52, v53 offset1:1
	s_waitcnt vmcnt(13)
	ds_write2_b32 v105, v62, v63 offset1:1
	ds_write2_b32 v106, v64, v65 offset1:1
	s_waitcnt vmcnt(12)
	ds_write2_b32 v107, v58, v59 offset1:1
	ds_write2_b32 v108, v60, v61 offset1:1
	s_waitcnt lgkmcnt(0)
	ds_read2_b32 v[22:23], v1 offset1:8
	ds_read2_b32 v[34:35], v1 offset0:33 offset1:41
	ds_read2_b32 v[36:37], v1 offset0:66 offset1:74
	ds_read2_b32 v[38:39], v1 offset0:99 offset1:107
	ds_read2_b32 v[40:41], v1 offset0:132 offset1:140
	s_waitcnt lgkmcnt(4)
	v_bfe_u32 v18, v22, 16, 1
	v_add3_u32 v18, v22, v18, s10
	s_waitcnt lgkmcnt(3)
	v_bfe_u32 v19, v34, 16, 1
	v_lshrrev_b32_e32 v18, 16, v18
	v_add3_u32 v19, v34, v19, s10
	ds_read2_b32 v[50:51], v1 offset0:165 offset1:173
	v_and_or_b32 v18, v19, s11, v18
	s_waitcnt lgkmcnt(3)
	v_bfe_u32 v19, v36, 16, 1
	v_add3_u32 v19, v36, v19, s10
	s_waitcnt lgkmcnt(2)
	v_bfe_u32 v20, v38, 16, 1
	ds_read2_b32 v[52:53], v1 offset0:198 offset1:206
	v_lshrrev_b32_e32 v19, 16, v19
	v_add3_u32 v20, v38, v20, s10
	ds_read2_b32 v[54:55], v1 offset0:231 offset1:239
	v_and_or_b32 v19, v20, s11, v19
	s_waitcnt lgkmcnt(3)
	v_bfe_u32 v20, v40, 16, 1
	v_add3_u32 v20, v40, v20, s10
	s_waitcnt lgkmcnt(2)
	v_bfe_u32 v21, v50, 16, 1
	v_lshrrev_b32_e32 v20, 16, v20
	v_add3_u32 v21, v50, v21, s10
	v_and_or_b32 v20, v21, s11, v20
	s_waitcnt lgkmcnt(1)
	v_bfe_u32 v21, v52, 16, 1
	v_add3_u32 v21, v52, v21, s10
	s_waitcnt lgkmcnt(0)
	v_bfe_u32 v22, v54, 16, 1
	v_lshl_add_u64 v[24:25], s[2:3], 0, v[92:93]
	v_lshrrev_b32_e32 v21, 16, v21
	v_add3_u32 v22, v54, v22, s10
	v_and_or_b32 v21, v22, s11, v21
	v_lshl_add_u64 v[56:57], v[24:25], 0, v[84:85]
	global_store_dwordx4 v[56:57], v[18:21], off
	v_bfe_u32 v22, v55, 16, 1
	v_add3_u32 v34, v55, v22, s10
	v_bfe_u32 v18, v23, 16, 1
	v_add3_u32 v18, v23, v18, s10
	v_bfe_u32 v19, v35, 16, 1
	v_lshrrev_b32_e32 v18, 16, v18
	v_add3_u32 v19, v35, v19, s10
	v_and_or_b32 v18, v19, s11, v18
	v_bfe_u32 v19, v37, 16, 1
	v_add3_u32 v19, v37, v19, s10
	v_bfe_u32 v20, v39, 16, 1
	v_lshrrev_b32_e32 v19, 16, v19
	v_add3_u32 v20, v39, v20, s10
	v_and_or_b32 v19, v20, s11, v19
	v_bfe_u32 v20, v41, 16, 1
	v_add3_u32 v20, v41, v20, s10
	v_bfe_u32 v21, v51, 16, 1
	v_lshrrev_b32_e32 v20, 16, v20
	v_add3_u32 v21, v51, v21, s10
	v_and_or_b32 v20, v21, s11, v20
	v_bfe_u32 v21, v53, 16, 1
	v_add3_u32 v21, v53, v21, s10
	v_lshrrev_b32_e32 v21, 16, v21
	ds_read2_b32 v[22:23], v1 offset0:16 offset1:24
	v_and_or_b32 v21, v34, s11, v21
	v_lshl_add_u64 v[34:35], v[24:25], 0, v[86:87]
	global_store_dwordx4 v[34:35], v[18:21], off
	ds_read2_b32 v[34:35], v1 offset0:49 offset1:57
	ds_read2_b32 v[36:37], v1 offset0:82 offset1:90
	ds_read2_b32 v[38:39], v1 offset0:115 offset1:123
	s_waitcnt lgkmcnt(3)
	v_bfe_u32 v18, v22, 16, 1
	v_add3_u32 v18, v22, v18, s10
	s_waitcnt lgkmcnt(2)
	v_bfe_u32 v19, v34, 16, 1
	ds_read2_b32 v[40:41], v1 offset0:148 offset1:156
	v_lshrrev_b32_e32 v18, 16, v18
	v_add3_u32 v19, v34, v19, s10
	ds_read2_b32 v[50:51], v1 offset0:181 offset1:189
	v_and_or_b32 v18, v19, s11, v18
	s_waitcnt lgkmcnt(3)
	v_bfe_u32 v19, v36, 16, 1
	v_add3_u32 v19, v36, v19, s10
	s_waitcnt lgkmcnt(2)
	v_bfe_u32 v20, v38, 16, 1
	ds_read2_b32 v[52:53], v1 offset0:214 offset1:222
	v_lshrrev_b32_e32 v19, 16, v19
	v_add3_u32 v20, v38, v20, s10
	ds_read2_b32 v[54:55], v1 offset0:247 offset1:255
	v_and_or_b32 v19, v20, s11, v19
	s_waitcnt lgkmcnt(3)
	v_bfe_u32 v20, v40, 16, 1
	v_add3_u32 v20, v40, v20, s10
	s_waitcnt lgkmcnt(2)
	v_bfe_u32 v21, v50, 16, 1
	v_lshrrev_b32_e32 v20, 16, v20
	v_add3_u32 v21, v50, v21, s10
	v_and_or_b32 v20, v21, s11, v20
	s_waitcnt lgkmcnt(1)
	v_bfe_u32 v21, v52, 16, 1
	v_add3_u32 v21, v52, v21, s10
	s_waitcnt lgkmcnt(0)
	v_bfe_u32 v22, v54, 16, 1
	v_lshrrev_b32_e32 v21, 16, v21
	v_add3_u32 v22, v54, v22, s10
	v_and_or_b32 v21, v22, s11, v21
	v_lshl_add_u64 v[56:57], v[24:25], 0, v[88:89]
	global_store_dwordx4 v[56:57], v[18:21], off
	s_add_u32 s4, s8, s13
	s_addc_u32 s5, s9, 0
	v_bfe_u32 v18, v23, 16, 1
	v_add3_u32 v18, v23, v18, s10
	v_bfe_u32 v19, v35, 16, 1
	v_lshrrev_b32_e32 v18, 16, v18
	v_add3_u32 v19, v35, v19, s10
	v_and_or_b32 v18, v19, s11, v18
	v_bfe_u32 v19, v37, 16, 1
	v_add3_u32 v19, v37, v19, s10
	v_bfe_u32 v20, v39, 16, 1
	s_lshl_b32 s7, s7, 1
	v_lshrrev_b32_e32 v19, 16, v19
	v_add3_u32 v20, v39, v20, s10
	s_add_u32 s4, s4, s7
	v_and_or_b32 v19, v20, s11, v19
	v_bfe_u32 v20, v41, 16, 1
	s_addc_u32 s5, s5, 0
	v_add3_u32 v20, v41, v20, s10
	v_bfe_u32 v21, v51, 16, 1
	s_add_i32 s6, s6, 7
	v_lshrrev_b32_e32 v20, 16, v20
	v_add3_u32 v21, v51, v21, s10
	s_and_b32 s2, s6, 0x3fc0
	s_lshl_b32 s3, s6, 5
	v_and_or_b32 v20, v21, s11, v20
	v_bfe_u32 v21, v53, 16, 1
	s_and_b32 s3, s3, 0x7e0
	s_lshl_b32 s6, s2, 13
	v_add3_u32 v21, v53, v21, s10
	v_bfe_u32 v22, v55, 16, 1
	s_add_u32 s6, s86, s6
	v_lshrrev_b32_e32 v21, 16, v21
	v_add3_u32 v22, v55, v22, s10
	s_addc_u32 s7, s87, 0
	s_lshl_b32 s12, s3, 2
	v_and_or_b32 v21, v22, s11, v21
	v_lshl_add_u64 v[22:23], v[24:25], 0, v[90:91]
	s_add_u32 s6, s6, s12
	global_store_dwordx4 v[22:23], v[18:21], off
	s_addc_u32 s7, s7, 0
	s_waitcnt lgkmcnt(0)
	s_mulk_i32 s3, 0x2c00
	v_lshl_add_u64 v[18:19], s[6:7], 0, v[68:69]
	v_lshl_add_u64 v[34:35], v[18:19], 0, v[66:67]
	v_lshl_add_u64 v[18:19], s[6:7], 0, v[70:71]
	v_lshl_add_u64 v[36:37], v[18:19], 0, v[66:67]
	global_load_dwordx4 v[18:21], v[34:35], off nt
	global_load_dwordx4 v[22:25], v[36:37], off nt
	v_lshl_add_u64 v[34:35], s[6:7], 0, v[72:73]
	v_lshl_add_u64 v[50:51], v[34:35], 0, v[66:67]
	v_lshl_add_u64 v[34:35], s[6:7], 0, v[74:75]
	v_lshl_add_u64 v[52:53], v[34:35], 0, v[66:67]
	global_load_dwordx4 v[34:37], v[50:51], off nt
	global_load_dwordx4 v[38:41], v[52:53], off nt
	v_lshl_add_u64 v[50:51], s[6:7], 0, v[76:77]
	v_lshl_add_u64 v[58:59], v[50:51], 0, v[66:67]
	v_lshl_add_u64 v[50:51], s[6:7], 0, v[78:79]
	v_lshl_add_u64 v[60:61], v[50:51], 0, v[66:67]
	global_load_dwordx4 v[50:53], v[58:59], off nt
	global_load_dwordx4 v[54:57], v[60:61], off nt
	v_lshl_add_u64 v[58:59], s[6:7], 0, v[80:81]
	v_lshl_add_u64 v[110:111], v[58:59], 0, v[66:67]
	v_lshl_add_u64 v[58:59], s[6:7], 0, v[82:83]
	v_lshl_add_u64 v[112:113], v[58:59], 0, v[66:67]
	global_load_dwordx4 v[58:61], v[110:111], off nt
	global_load_dwordx4 v[62:65], v[112:113], off nt
	s_waitcnt vmcnt(19)
	ds_write2_b32 v94, v6, v7 offset1:1
	ds_write2_b32 v94, v8, v9 offset0:2 offset1:3
	s_waitcnt vmcnt(18)
	ds_write2_b32 v95, v2, v3 offset1:1
	ds_write2_b32 v96, v4, v5 offset1:1
	s_waitcnt vmcnt(17)
	ds_write2_b32 v97, v14, v15 offset1:1
	ds_write2_b32 v98, v16, v17 offset1:1
	s_waitcnt vmcnt(16)
	ds_write2_b32 v99, v10, v11 offset1:1
	ds_write2_b32 v100, v12, v13 offset1:1
	s_waitcnt vmcnt(15)
	ds_write2_b32 v101, v30, v31 offset1:1
	ds_write2_b32 v102, v32, v33 offset1:1
	s_waitcnt vmcnt(14)
	ds_write2_b32 v103, v26, v27 offset1:1
	ds_write2_b32 v104, v28, v29 offset1:1
	s_waitcnt vmcnt(13)
	ds_write2_b32 v105, v46, v47 offset1:1
	ds_write2_b32 v106, v48, v49 offset1:1
	s_waitcnt vmcnt(12)
	ds_write2_b32 v107, v42, v43 offset1:1
	ds_write2_b32 v108, v44, v45 offset1:1
	s_waitcnt lgkmcnt(0)
	ds_read2_b32 v[6:7], v1 offset1:8
	ds_read2_b32 v[10:11], v1 offset0:33 offset1:41
	ds_read2_b32 v[12:13], v1 offset0:66 offset1:74
	ds_read2_b32 v[14:15], v1 offset0:99 offset1:107
	ds_read2_b32 v[16:17], v1 offset0:132 offset1:140
	s_waitcnt lgkmcnt(4)
	v_bfe_u32 v2, v6, 16, 1
	v_add3_u32 v2, v6, v2, s10
	s_waitcnt lgkmcnt(3)
	v_bfe_u32 v3, v10, 16, 1
	v_lshrrev_b32_e32 v2, 16, v2
	v_add3_u32 v3, v10, v3, s10
	ds_read2_b32 v[26:27], v1 offset0:165 offset1:173
	v_and_or_b32 v2, v3, s11, v2
	s_waitcnt lgkmcnt(3)
	v_bfe_u32 v3, v12, 16, 1
	v_add3_u32 v3, v12, v3, s10
	s_waitcnt lgkmcnt(2)
	v_bfe_u32 v4, v14, 16, 1
	ds_read2_b32 v[28:29], v1 offset0:198 offset1:206
	v_lshrrev_b32_e32 v3, 16, v3
	v_add3_u32 v4, v14, v4, s10
	ds_read2_b32 v[30:31], v1 offset0:231 offset1:239
	v_and_or_b32 v3, v4, s11, v3
	s_waitcnt lgkmcnt(3)
	v_bfe_u32 v4, v16, 16, 1
	v_add3_u32 v4, v16, v4, s10
	s_waitcnt lgkmcnt(2)
	v_bfe_u32 v5, v26, 16, 1
	v_lshrrev_b32_e32 v4, 16, v4
	v_add3_u32 v5, v26, v5, s10
	v_and_or_b32 v4, v5, s11, v4
	s_waitcnt lgkmcnt(1)
	v_bfe_u32 v5, v28, 16, 1
	v_add3_u32 v5, v28, v5, s10
	s_waitcnt lgkmcnt(0)
	v_bfe_u32 v6, v30, 16, 1
	v_lshl_add_u64 v[8:9], s[4:5], 0, v[92:93]
	v_lshrrev_b32_e32 v5, 16, v5
	v_add3_u32 v6, v30, v6, s10
	v_and_or_b32 v5, v6, s11, v5
	v_lshl_add_u64 v[32:33], v[8:9], 0, v[84:85]
	global_store_dwordx4 v[32:33], v[2:5], off
	v_bfe_u32 v6, v31, 16, 1
	v_add3_u32 v10, v31, v6, s10
	v_bfe_u32 v2, v7, 16, 1
	v_add3_u32 v2, v7, v2, s10
	v_bfe_u32 v3, v11, 16, 1
	v_lshrrev_b32_e32 v2, 16, v2
	v_add3_u32 v3, v11, v3, s10
	v_and_or_b32 v2, v3, s11, v2
	v_bfe_u32 v3, v13, 16, 1
	v_add3_u32 v3, v13, v3, s10
	v_bfe_u32 v4, v15, 16, 1
	v_lshrrev_b32_e32 v3, 16, v3
	v_add3_u32 v4, v15, v4, s10
	v_and_or_b32 v3, v4, s11, v3
	v_bfe_u32 v4, v17, 16, 1
	v_add3_u32 v4, v17, v4, s10
	v_bfe_u32 v5, v27, 16, 1
	v_lshrrev_b32_e32 v4, 16, v4
	v_add3_u32 v5, v27, v5, s10
	v_and_or_b32 v4, v5, s11, v4
	v_bfe_u32 v5, v29, 16, 1
	v_add3_u32 v5, v29, v5, s10
	v_lshrrev_b32_e32 v5, 16, v5
	ds_read2_b32 v[6:7], v1 offset0:16 offset1:24
	v_and_or_b32 v5, v10, s11, v5
	v_lshl_add_u64 v[10:11], v[8:9], 0, v[86:87]
	global_store_dwordx4 v[10:11], v[2:5], off
	ds_read2_b32 v[10:11], v1 offset0:49 offset1:57
	ds_read2_b32 v[12:13], v1 offset0:82 offset1:90
	ds_read2_b32 v[14:15], v1 offset0:115 offset1:123
	s_waitcnt lgkmcnt(3)
	v_bfe_u32 v2, v6, 16, 1
	v_add3_u32 v2, v6, v2, s10
	s_waitcnt lgkmcnt(2)
	v_bfe_u32 v3, v10, 16, 1
	ds_read2_b32 v[16:17], v1 offset0:148 offset1:156
	v_lshrrev_b32_e32 v2, 16, v2
	v_add3_u32 v3, v10, v3, s10
	ds_read2_b32 v[26:27], v1 offset0:181 offset1:189
	v_and_or_b32 v2, v3, s11, v2
	s_waitcnt lgkmcnt(3)
	v_bfe_u32 v3, v12, 16, 1
	v_add3_u32 v3, v12, v3, s10
	s_waitcnt lgkmcnt(2)
	v_bfe_u32 v4, v14, 16, 1
	ds_read2_b32 v[28:29], v1 offset0:214 offset1:222
	v_lshrrev_b32_e32 v3, 16, v3
	v_add3_u32 v4, v14, v4, s10
	ds_read2_b32 v[30:31], v1 offset0:247 offset1:255
	v_and_or_b32 v3, v4, s11, v3
	s_waitcnt lgkmcnt(3)
	v_bfe_u32 v4, v16, 16, 1
	v_add3_u32 v4, v16, v4, s10
	s_waitcnt lgkmcnt(2)
	v_bfe_u32 v5, v26, 16, 1
	v_lshrrev_b32_e32 v4, 16, v4
	v_add3_u32 v5, v26, v5, s10
	v_and_or_b32 v4, v5, s11, v4
	s_waitcnt lgkmcnt(1)
	v_bfe_u32 v5, v28, 16, 1
	v_add3_u32 v5, v28, v5, s10
	s_waitcnt lgkmcnt(0)
	v_bfe_u32 v6, v30, 16, 1
	v_lshrrev_b32_e32 v5, 16, v5
	v_add3_u32 v6, v30, v6, s10
	v_and_or_b32 v5, v6, s11, v5
	v_lshl_add_u64 v[32:33], v[8:9], 0, v[88:89]
	global_store_dwordx4 v[32:33], v[2:5], off
	v_bfe_u32 v6, v31, 16, 1
	v_add3_u32 v6, v31, v6, s10
	v_bfe_u32 v2, v7, 16, 1
	v_add3_u32 v2, v7, v2, s10
	v_bfe_u32 v3, v11, 16, 1
	v_lshrrev_b32_e32 v2, 16, v2
	v_add3_u32 v3, v11, v3, s10
	v_and_or_b32 v2, v3, s11, v2
	v_bfe_u32 v3, v13, 16, 1
	v_add3_u32 v3, v13, v3, s10
	v_bfe_u32 v4, v15, 16, 1
	v_lshrrev_b32_e32 v3, 16, v3
	v_add3_u32 v4, v15, v4, s10
	v_and_or_b32 v3, v4, s11, v3
	v_bfe_u32 v4, v17, 16, 1
	v_add3_u32 v4, v17, v4, s10
	v_bfe_u32 v5, v27, 16, 1
	v_lshrrev_b32_e32 v4, 16, v4
	v_add3_u32 v5, v27, v5, s10
	v_and_or_b32 v4, v5, s11, v4
	v_bfe_u32 v5, v29, 16, 1
	v_add3_u32 v5, v29, v5, s10
	v_lshrrev_b32_e32 v5, 16, v5
	v_and_or_b32 v5, v6, s11, v5
	v_lshl_add_u64 v[6:7], v[8:9], 0, v[90:91]
	global_store_dwordx4 v[6:7], v[2:5], off
	s_waitcnt lgkmcnt(0)
	s_waitcnt vmcnt(11)
	ds_write2_b32 v94, v18, v19 offset1:1
	ds_write2_b32 v94, v20, v21 offset0:2 offset1:3
	s_waitcnt vmcnt(10)
	ds_write2_b32 v95, v22, v23 offset1:1
	ds_write2_b32 v96, v24, v25 offset1:1
	s_waitcnt vmcnt(9)
	ds_write2_b32 v97, v34, v35 offset1:1
	ds_write2_b32 v98, v36, v37 offset1:1
	s_waitcnt vmcnt(8)
	ds_write2_b32 v99, v38, v39 offset1:1
	ds_write2_b32 v100, v40, v41 offset1:1
	s_waitcnt vmcnt(7)
	ds_write2_b32 v101, v50, v51 offset1:1
	ds_write2_b32 v102, v52, v53 offset1:1
	s_waitcnt vmcnt(6)
	ds_write2_b32 v103, v54, v55 offset1:1
	ds_write2_b32 v104, v56, v57 offset1:1
	s_waitcnt vmcnt(5)
	ds_write2_b32 v105, v58, v59 offset1:1
	ds_write2_b32 v106, v60, v61 offset1:1
	s_waitcnt vmcnt(4)
	ds_write2_b32 v107, v62, v63 offset1:1
	ds_write2_b32 v108, v64, v65 offset1:1
	s_waitcnt lgkmcnt(0)
	ds_read2_b32 v[6:7], v1 offset1:8
	ds_read2_b32 v[10:11], v1 offset0:33 offset1:41
	ds_read2_b32 v[12:13], v1 offset0:66 offset1:74
	ds_read2_b32 v[14:15], v1 offset0:99 offset1:107
	ds_read2_b32 v[16:17], v1 offset0:132 offset1:140
	s_waitcnt lgkmcnt(4)
	v_bfe_u32 v2, v6, 16, 1
	v_add3_u32 v2, v6, v2, s10
	s_waitcnt lgkmcnt(3)
	v_bfe_u32 v3, v10, 16, 1
	v_lshrrev_b32_e32 v2, 16, v2
	v_add3_u32 v3, v10, v3, s10
	ds_read2_b32 v[18:19], v1 offset0:165 offset1:173
	v_and_or_b32 v2, v3, s11, v2
	s_waitcnt lgkmcnt(3)
	v_bfe_u32 v3, v12, 16, 1
	v_add3_u32 v3, v12, v3, s10
	s_waitcnt lgkmcnt(2)
	v_bfe_u32 v4, v14, 16, 1
	ds_read2_b32 v[20:21], v1 offset0:198 offset1:206
	v_lshrrev_b32_e32 v3, 16, v3
	v_add3_u32 v4, v14, v4, s10
	ds_read2_b32 v[22:23], v1 offset0:231 offset1:239
	v_and_or_b32 v3, v4, s11, v3
	s_waitcnt lgkmcnt(3)
	v_bfe_u32 v4, v16, 16, 1
	s_add_u32 s3, s8, s3
	v_add3_u32 v4, v16, v4, s10
	s_waitcnt lgkmcnt(2)
	v_bfe_u32 v5, v18, 16, 1
	s_addc_u32 s4, s9, 0
	s_lshl_b32 s2, s2, 1
	v_lshrrev_b32_e32 v4, 16, v4
	v_add3_u32 v5, v18, v5, s10
	s_add_u32 s2, s3, s2
	v_and_or_b32 v4, v5, s11, v4
	s_waitcnt lgkmcnt(1)
	v_bfe_u32 v5, v20, 16, 1
	s_addc_u32 s3, s4, 0
	v_add3_u32 v5, v20, v5, s10
	s_waitcnt lgkmcnt(0)
	v_bfe_u32 v6, v22, 16, 1
	v_lshl_add_u64 v[8:9], s[2:3], 0, v[92:93]
	v_lshrrev_b32_e32 v5, 16, v5
	v_add3_u32 v6, v22, v6, s10
	v_and_or_b32 v5, v6, s11, v5
	v_lshl_add_u64 v[24:25], v[8:9], 0, v[84:85]
	global_store_dwordx4 v[24:25], v[2:5], off
	v_bfe_u32 v6, v23, 16, 1
	v_add3_u32 v10, v23, v6, s10
	v_bfe_u32 v2, v7, 16, 1
	v_add3_u32 v2, v7, v2, s10
	v_bfe_u32 v3, v11, 16, 1
	v_lshrrev_b32_e32 v2, 16, v2
	v_add3_u32 v3, v11, v3, s10
	v_and_or_b32 v2, v3, s11, v2
	v_bfe_u32 v3, v13, 16, 1
	v_add3_u32 v3, v13, v3, s10
	v_bfe_u32 v4, v15, 16, 1
	v_lshrrev_b32_e32 v3, 16, v3
	v_add3_u32 v4, v15, v4, s10
	v_and_or_b32 v3, v4, s11, v3
	v_bfe_u32 v4, v17, 16, 1
	v_add3_u32 v4, v17, v4, s10
	v_bfe_u32 v5, v19, 16, 1
	v_lshrrev_b32_e32 v4, 16, v4
	v_add3_u32 v5, v19, v5, s10
	v_and_or_b32 v4, v5, s11, v4
	v_bfe_u32 v5, v21, 16, 1
	v_add3_u32 v5, v21, v5, s10
	v_lshrrev_b32_e32 v5, 16, v5
	ds_read2_b32 v[6:7], v1 offset0:16 offset1:24
	v_and_or_b32 v5, v10, s11, v5
	v_lshl_add_u64 v[10:11], v[8:9], 0, v[86:87]
	global_store_dwordx4 v[10:11], v[2:5], off
	ds_read2_b32 v[10:11], v1 offset0:49 offset1:57
	ds_read2_b32 v[12:13], v1 offset0:82 offset1:90
	ds_read2_b32 v[14:15], v1 offset0:115 offset1:123
	s_waitcnt lgkmcnt(3)
	v_bfe_u32 v2, v6, 16, 1
	v_add3_u32 v2, v6, v2, s10
	s_waitcnt lgkmcnt(2)
	v_bfe_u32 v3, v10, 16, 1
	ds_read2_b32 v[16:17], v1 offset0:148 offset1:156
	v_lshrrev_b32_e32 v2, 16, v2
	v_add3_u32 v3, v10, v3, s10
	ds_read2_b32 v[18:19], v1 offset0:181 offset1:189
	v_and_or_b32 v2, v3, s11, v2
	s_waitcnt lgkmcnt(3)
	v_bfe_u32 v3, v12, 16, 1
	v_add3_u32 v3, v12, v3, s10
	s_waitcnt lgkmcnt(2)
	v_bfe_u32 v4, v14, 16, 1
	ds_read2_b32 v[20:21], v1 offset0:214 offset1:222
	v_lshrrev_b32_e32 v3, 16, v3
	v_add3_u32 v4, v14, v4, s10
	ds_read2_b32 v[22:23], v1 offset0:247 offset1:255
	v_and_or_b32 v3, v4, s11, v3
	s_waitcnt lgkmcnt(3)
	v_bfe_u32 v4, v16, 16, 1
	v_add3_u32 v4, v16, v4, s10
	s_waitcnt lgkmcnt(2)
	v_bfe_u32 v5, v18, 16, 1
	v_lshrrev_b32_e32 v4, 16, v4
	v_add3_u32 v5, v18, v5, s10
	v_and_or_b32 v4, v5, s11, v4
	s_waitcnt lgkmcnt(1)
	v_bfe_u32 v5, v20, 16, 1
	v_add3_u32 v5, v20, v5, s10
	s_waitcnt lgkmcnt(0)
	v_bfe_u32 v6, v22, 16, 1
	v_lshrrev_b32_e32 v5, 16, v5
	v_add3_u32 v6, v22, v6, s10
	v_and_or_b32 v5, v6, s11, v5
	v_lshl_add_u64 v[24:25], v[8:9], 0, v[88:89]
	global_store_dwordx4 v[24:25], v[2:5], off
	v_bfe_u32 v6, v23, 16, 1
	v_add3_u32 v6, v23, v6, s10
	v_bfe_u32 v2, v7, 16, 1
	v_add3_u32 v2, v7, v2, s10
	v_bfe_u32 v3, v11, 16, 1
	v_lshrrev_b32_e32 v2, 16, v2
	v_add3_u32 v3, v11, v3, s10
	v_and_or_b32 v2, v3, s11, v2
	v_bfe_u32 v3, v13, 16, 1
	v_add3_u32 v3, v13, v3, s10
	v_bfe_u32 v4, v15, 16, 1
	v_lshrrev_b32_e32 v3, 16, v3
	v_add3_u32 v4, v15, v4, s10
	v_and_or_b32 v3, v4, s11, v3
	v_bfe_u32 v4, v17, 16, 1
	v_add3_u32 v4, v17, v4, s10
	v_bfe_u32 v5, v19, 16, 1
	v_lshrrev_b32_e32 v4, 16, v4
	v_add3_u32 v5, v19, v5, s10
	v_and_or_b32 v4, v5, s11, v4
	v_bfe_u32 v5, v21, 16, 1
	v_add3_u32 v5, v21, v5, s10
	v_lshrrev_b32_e32 v5, 16, v5
	v_and_or_b32 v5, v6, s11, v5
	v_lshl_add_u64 v[6:7], v[8:9], 0, v[90:91]
	global_store_dwordx4 v[6:7], v[2:5], off
	s_waitcnt lgkmcnt(0)
	s_mov_b64 s[2:3], 0
	s_branch .LBB0_1143
